# v108 plus the four individually neutral edits combined: native bf16 cvt in GLA D stage, chain-wave private latch, loop-top scalar block moved to phase 2, static prio raise for waves 4-7
# speedup vs baseline: 1.0141x; 1.0052x over previous
.Lprio_y0:
.LBB0_197:
	ds_read_b128 v[144:147], v151
	ds_read_b128 v[154:157], v151 offset:1024
	ds_read_b128 v[158:161], v151 offset:2048
	ds_read_b128 v[162:165], v151 offset:3072
	s_add_i32 m0, s24, 0xc000
	ds_read_b128 v[166:169], v152
	ds_read_b128 v[170:173], v152 offset:1024
	ds_read_b128 v[174:177], v152 offset:2048
	ds_read_b128 v[178:181], v152 offset:3072
	ds_read_b128 v[182:185], v152 offset:4096
	ds_read_b128 v[186:189], v152 offset:5120
	ds_read_b128 v[190:193], v152 offset:6144
	ds_read_b128 v[194:197], v152 offset:7168
	global_load_lds_dwordx4 v136, s[16:17]
	s_add_i32 m0, s24, 0xe000
	s_nop 0
	global_load_lds_dwordx4 v138, s[16:17]
	s_waitcnt lgkmcnt(8)
	s_barrier
	s_waitcnt lgkmcnt(0)
	v_mfma_f32_16x16x32_f16 v[124:127], v[144:147], v[166:169], v[124:127]
	v_mfma_f32_16x16x32_f16 v[120:123], v[158:161], v[166:169], v[120:123]
	v_mfma_f32_16x16x32_f16 v[108:111], v[144:147], v[174:177], v[108:111]
	v_mfma_f32_16x16x32_f16 v[104:107], v[158:161], v[174:177], v[104:107]
	v_mfma_f32_16x16x32_f16 v[92:95], v[144:147], v[182:185], v[92:95]
	v_mfma_f32_16x16x32_f16 v[88:91], v[158:161], v[182:185], v[88:91]
	v_mfma_f32_16x16x32_f16 v[76:79], v[144:147], v[190:193], v[76:79]
	v_mfma_f32_16x16x32_f16 v[72:75], v[158:161], v[190:193], v[72:75]
	v_mfma_f32_16x16x32_f16 v[124:127], v[154:157], v[170:173], v[124:127]
	v_mfma_f32_16x16x32_f16 v[120:123], v[162:165], v[170:173], v[120:123]
	v_mfma_f32_16x16x32_f16 v[108:111], v[154:157], v[178:181], v[108:111]
	v_mfma_f32_16x16x32_f16 v[104:107], v[162:165], v[178:181], v[104:107]
	v_mfma_f32_16x16x32_f16 v[92:95], v[154:157], v[186:189], v[92:95]
	v_mfma_f32_16x16x32_f16 v[88:91], v[162:165], v[186:189], v[88:91]
	v_mfma_f32_16x16x32_f16 v[76:79], v[154:157], v[194:197], v[76:79]
	v_mfma_f32_16x16x32_f16 v[72:75], v[162:165], v[194:197], v[72:75]
	s_barrier
	s_add_u32 s18, s16, 0xfff80080
	s_addc_u32 s19, s17, -1
	s_cmp_eq_u32 s78, 28
	s_cselect_b32 s21, s5, s19
	s_cselect_b32 s20, s9, s18
	s_cselect_b32 s19, s7, s77
	s_cselect_b32 s18, s15, s76
	s_add_i32 s79, s68, s23
	s_add_u32 s72, s18, s0
	s_addc_u32 s73, s19, s1
	s_mov_b32 m0, s79
	ds_read_b128 v[198:201], v153
	ds_read_b128 v[202:205], v153 offset:1024
	ds_read_b128 v[206:209], v153 offset:2048
	ds_read_b128 v[210:213], v153 offset:3072
	global_load_lds_dwordx4 v130, s[18:19]
	s_add_i32 m0, s79, 0x2000
	s_nop 0
	global_load_lds_dwordx4 v134, s[18:19]
	s_barrier
	s_waitcnt lgkmcnt(0)
	v_mfma_f32_16x16x32_f16 v[116:119], v[198:201], v[166:169], v[116:119]
	v_mfma_f32_16x16x32_f16 v[112:115], v[206:209], v[166:169], v[112:115]
	v_mfma_f32_16x16x32_f16 v[100:103], v[198:201], v[174:177], v[100:103]
	v_mfma_f32_16x16x32_f16 v[96:99], v[206:209], v[174:177], v[96:99]
	v_mfma_f32_16x16x32_f16 v[84:87], v[198:201], v[182:185], v[84:87]
	v_mfma_f32_16x16x32_f16 v[80:83], v[206:209], v[182:185], v[80:83]
	v_mfma_f32_16x16x32_f16 v[68:71], v[198:201], v[190:193], v[68:71]
	v_mfma_f32_16x16x32_f16 v[64:67], v[206:209], v[190:193], v[64:67]
	v_mfma_f32_16x16x32_f16 v[116:119], v[202:205], v[170:173], v[116:119]
	v_mfma_f32_16x16x32_f16 v[112:115], v[210:213], v[170:173], v[112:115]
	v_mfma_f32_16x16x32_f16 v[100:103], v[202:205], v[178:181], v[100:103]
	v_mfma_f32_16x16x32_f16 v[96:99], v[210:213], v[178:181], v[96:99]
	v_mfma_f32_16x16x32_f16 v[84:87], v[202:205], v[186:189], v[84:87]
	v_mfma_f32_16x16x32_f16 v[80:83], v[210:213], v[186:189], v[80:83]
	v_mfma_f32_16x16x32_f16 v[68:71], v[202:205], v[194:197], v[68:71]
	v_mfma_f32_16x16x32_f16 v[64:67], v[210:213], v[194:197], v[64:67]
	s_barrier
	s_mov_b32 m0, s24
	s_add_u32 s74, s20, s0
	s_addc_u32 s75, s21, s1
	ds_read_b128 v[166:169], v152 offset:16384
	ds_read_b128 v[170:173], v152 offset:17408
	ds_read_b128 v[174:177], v152 offset:18432
	ds_read_b128 v[178:181], v152 offset:19456
	ds_read_b128 v[182:185], v152 offset:20480
	ds_read_b128 v[186:189], v152 offset:21504
	ds_read_b128 v[190:193], v152 offset:22528
	ds_read_b128 v[194:197], v152 offset:23552
	global_load_lds_dwordx4 v128, s[20:21]
	s_mov_b32 m0, s25
	s_nop 0
	global_load_lds_dwordx4 v132, s[20:21]
	s_barrier
	s_waitcnt lgkmcnt(0)
	v_mfma_f32_16x16x32_f16 v[60:63], v[144:147], v[166:169], v[60:63]
	v_mfma_f32_16x16x32_f16 v[56:59], v[158:161], v[166:169], v[56:59]
	v_mfma_f32_16x16x32_f16 v[44:47], v[144:147], v[174:177], v[44:47]
	v_mfma_f32_16x16x32_f16 v[40:43], v[158:161], v[174:177], v[40:43]
	v_mfma_f32_16x16x32_f16 v[28:31], v[144:147], v[182:185], v[28:31]
	v_mfma_f32_16x16x32_f16 v[24:27], v[158:161], v[182:185], v[24:27]
	v_mfma_f32_16x16x32_f16 v[12:15], v[144:147], v[190:193], v[12:15]
	v_mfma_f32_16x16x32_f16 v[8:11], v[158:161], v[190:193], v[8:11]
	v_mfma_f32_16x16x32_f16 v[60:63], v[154:157], v[170:173], v[60:63]
	v_mfma_f32_16x16x32_f16 v[56:59], v[162:165], v[170:173], v[56:59]
	v_mfma_f32_16x16x32_f16 v[44:47], v[154:157], v[178:181], v[44:47]
	v_mfma_f32_16x16x32_f16 v[40:43], v[162:165], v[178:181], v[40:43]
	v_mfma_f32_16x16x32_f16 v[28:31], v[154:157], v[186:189], v[28:31]
	v_mfma_f32_16x16x32_f16 v[24:27], v[162:165], v[186:189], v[24:27]
	v_mfma_f32_16x16x32_f16 v[12:15], v[154:157], v[194:197], v[12:15]
	v_mfma_f32_16x16x32_f16 v[8:11], v[162:165], v[194:197], v[8:11]
	s_barrier
	s_add_u32 s80, s18, 0x80000
	s_addc_u32 s81, s19, 0
	s_add_i32 s79, s69, s23
	s_mov_b32 m0, s79
	s_nop 0
	global_load_lds_dwordx4 v130, s[80:81]
	s_add_i32 m0, s79, 0x2000
	s_nop 0
	global_load_lds_dwordx4 v134, s[80:81]
	s_waitcnt vmcnt(6)
	s_barrier
	v_mfma_f32_16x16x32_f16 v[52:55], v[198:201], v[166:169], v[52:55]
	v_mfma_f32_16x16x32_f16 v[48:51], v[206:209], v[166:169], v[48:51]
	v_mfma_f32_16x16x32_f16 v[36:39], v[198:201], v[174:177], v[36:39]
	v_mfma_f32_16x16x32_f16 v[32:35], v[206:209], v[174:177], v[32:35]
	v_mfma_f32_16x16x32_f16 v[20:23], v[198:201], v[182:185], v[20:23]
	v_mfma_f32_16x16x32_f16 v[16:19], v[206:209], v[182:185], v[16:19]
	v_mfma_f32_16x16x32_f16 v[4:7], v[198:201], v[190:193], v[4:7]
	v_mfma_f32_16x16x32_f16 v[0:3], v[206:209], v[190:193], v[0:3]
	v_mfma_f32_16x16x32_f16 v[52:55], v[202:205], v[170:173], v[52:55]
	v_mfma_f32_16x16x32_f16 v[48:51], v[210:213], v[170:173], v[48:51]
	v_mfma_f32_16x16x32_f16 v[36:39], v[202:205], v[178:181], v[36:39]
	v_mfma_f32_16x16x32_f16 v[32:35], v[210:213], v[178:181], v[32:35]
	v_mfma_f32_16x16x32_f16 v[20:23], v[202:205], v[186:189], v[20:23]
	v_mfma_f32_16x16x32_f16 v[16:19], v[210:213], v[186:189], v[16:19]
	v_mfma_f32_16x16x32_f16 v[4:7], v[202:205], v[194:197], v[4:7]
	v_mfma_f32_16x16x32_f16 v[0:3], v[210:213], v[194:197], v[0:3]
	s_barrier
	s_add_i32 s79, 0, 0x18000
	v_add_u32_e32 v162, s79, v149
	ds_read_b128 v[144:147], v162
	ds_read_b128 v[154:157], v162 offset:1024
	ds_read_b128 v[158:161], v162 offset:2048
	ds_read_b128 v[162:165], v162 offset:3072
	s_add_u32 s20, s20, 0x80000
	s_addc_u32 s21, s21, 0
	s_mov_b32 m0, s26
	ds_read_b128 v[166:169], v152 offset:32768
	ds_read_b128 v[170:173], v152 offset:33792
	ds_read_b128 v[174:177], v152 offset:34816
	ds_read_b128 v[178:181], v152 offset:35840
	ds_read_b128 v[182:185], v152 offset:36864
	ds_read_b128 v[186:189], v152 offset:37888
	ds_read_b128 v[190:193], v152 offset:38912
	ds_read_b128 v[194:197], v152 offset:39936
	global_load_lds_dwordx4 v128, s[20:21]
	s_mov_b32 m0, s27
	s_nop 0
	global_load_lds_dwordx4 v132, s[20:21]
	s_waitcnt lgkmcnt(8)
	s_barrier
	s_waitcnt lgkmcnt(0)
	v_mfma_f32_16x16x32_f16 v[124:127], v[144:147], v[166:169], v[124:127]
	v_mfma_f32_16x16x32_f16 v[120:123], v[158:161], v[166:169], v[120:123]
	v_mfma_f32_16x16x32_f16 v[108:111], v[144:147], v[174:177], v[108:111]
	v_mfma_f32_16x16x32_f16 v[104:107], v[158:161], v[174:177], v[104:107]
	v_mfma_f32_16x16x32_f16 v[92:95], v[144:147], v[182:185], v[92:95]
	v_mfma_f32_16x16x32_f16 v[88:91], v[158:161], v[182:185], v[88:91]
	v_mfma_f32_16x16x32_f16 v[76:79], v[144:147], v[190:193], v[76:79]
	v_mfma_f32_16x16x32_f16 v[72:75], v[158:161], v[190:193], v[72:75]
	v_mfma_f32_16x16x32_f16 v[124:127], v[154:157], v[170:173], v[124:127]
	v_mfma_f32_16x16x32_f16 v[120:123], v[162:165], v[170:173], v[120:123]
	v_mfma_f32_16x16x32_f16 v[108:111], v[154:157], v[178:181], v[108:111]
	v_mfma_f32_16x16x32_f16 v[104:107], v[162:165], v[178:181], v[104:107]
	v_mfma_f32_16x16x32_f16 v[92:95], v[154:157], v[186:189], v[92:95]
	v_mfma_f32_16x16x32_f16 v[88:91], v[162:165], v[186:189], v[88:91]
	v_mfma_f32_16x16x32_f16 v[76:79], v[154:157], v[194:197], v[76:79]
	v_mfma_f32_16x16x32_f16 v[72:75], v[162:165], v[194:197], v[72:75]
	s_barrier
	s_add_i32 s20, 0, 0x1c000
	s_add_i32 s21, s79, s23
	v_add_u32_e32 v210, s20, v149
	s_mov_b32 m0, s21
	ds_read_b128 v[198:201], v210
	ds_read_b128 v[202:205], v210 offset:1024
	ds_read_b128 v[206:209], v210 offset:2048
	ds_read_b128 v[210:213], v210 offset:3072
	global_load_lds_dwordx4 v130, s[72:73]
	s_add_i32 m0, s21, 0x2000
	s_nop 0
	global_load_lds_dwordx4 v134, s[72:73]
	s_barrier
	s_waitcnt lgkmcnt(0)
	v_mfma_f32_16x16x32_f16 v[116:119], v[198:201], v[166:169], v[116:119]
	v_mfma_f32_16x16x32_f16 v[112:115], v[206:209], v[166:169], v[112:115]
	v_mfma_f32_16x16x32_f16 v[100:103], v[198:201], v[174:177], v[100:103]
	v_mfma_f32_16x16x32_f16 v[96:99], v[206:209], v[174:177], v[96:99]
	v_mfma_f32_16x16x32_f16 v[84:87], v[198:201], v[182:185], v[84:87]
	v_mfma_f32_16x16x32_f16 v[80:83], v[206:209], v[182:185], v[80:83]
	v_mfma_f32_16x16x32_f16 v[68:71], v[198:201], v[190:193], v[68:71]
	v_mfma_f32_16x16x32_f16 v[64:67], v[206:209], v[190:193], v[64:67]
	v_mfma_f32_16x16x32_f16 v[116:119], v[202:205], v[170:173], v[116:119]
	v_mfma_f32_16x16x32_f16 v[112:115], v[210:213], v[170:173], v[112:115]
	v_mfma_f32_16x16x32_f16 v[100:103], v[202:205], v[178:181], v[100:103]
	v_mfma_f32_16x16x32_f16 v[96:99], v[210:213], v[178:181], v[96:99]
	v_mfma_f32_16x16x32_f16 v[84:87], v[202:205], v[186:189], v[84:87]
	v_mfma_f32_16x16x32_f16 v[80:83], v[210:213], v[186:189], v[80:83]
	v_mfma_f32_16x16x32_f16 v[68:71], v[202:205], v[194:197], v[68:71]
	v_mfma_f32_16x16x32_f16 v[64:67], v[210:213], v[194:197], v[64:67]
	s_barrier
	s_mov_b32 m0, s29
	ds_read_b128 v[166:169], v152 offset:49152
	ds_read_b128 v[170:173], v152 offset:50176
	ds_read_b128 v[174:177], v152 offset:51200
	ds_read_b128 v[178:181], v152 offset:52224
	ds_read_b128 v[182:185], v152 offset:53248
	ds_read_b128 v[186:189], v152 offset:54272
	ds_read_b128 v[190:193], v152 offset:55296
	ds_read_b128 v[194:197], v152 offset:56320
	global_load_lds_dwordx4 v128, s[74:75]
	s_mov_b32 m0, s30
	s_nop 0
	global_load_lds_dwordx4 v132, s[74:75]
	s_barrier
	s_waitcnt lgkmcnt(0)
	v_mfma_f32_16x16x32_f16 v[60:63], v[144:147], v[166:169], v[60:63]
	v_mfma_f32_16x16x32_f16 v[56:59], v[158:161], v[166:169], v[56:59]
	v_mfma_f32_16x16x32_f16 v[44:47], v[144:147], v[174:177], v[44:47]
	v_mfma_f32_16x16x32_f16 v[40:43], v[158:161], v[174:177], v[40:43]
	v_mfma_f32_16x16x32_f16 v[28:31], v[144:147], v[182:185], v[28:31]
	v_mfma_f32_16x16x32_f16 v[24:27], v[158:161], v[182:185], v[24:27]
	v_mfma_f32_16x16x32_f16 v[12:15], v[144:147], v[190:193], v[12:15]
	v_mfma_f32_16x16x32_f16 v[8:11], v[158:161], v[190:193], v[8:11]
	v_mfma_f32_16x16x32_f16 v[60:63], v[154:157], v[170:173], v[60:63]
	v_mfma_f32_16x16x32_f16 v[56:59], v[162:165], v[170:173], v[56:59]
	v_mfma_f32_16x16x32_f16 v[44:47], v[154:157], v[178:181], v[44:47]
	v_mfma_f32_16x16x32_f16 v[40:43], v[162:165], v[178:181], v[40:43]
	v_mfma_f32_16x16x32_f16 v[28:31], v[154:157], v[186:189], v[28:31]
	v_mfma_f32_16x16x32_f16 v[24:27], v[162:165], v[186:189], v[24:27]
	v_mfma_f32_16x16x32_f16 v[12:15], v[154:157], v[194:197], v[12:15]
	v_mfma_f32_16x16x32_f16 v[8:11], v[162:165], v[194:197], v[8:11]
	s_barrier
	s_add_u32 s18, s18, 0x80080
	s_addc_u32 s19, s19, 0
	s_add_i32 s20, s20, s23
	s_mov_b32 m0, s20
	s_nop 0
	global_load_lds_dwordx4 v130, s[18:19]
	s_add_i32 m0, s20, 0x2000
	s_nop 0
	global_load_lds_dwordx4 v134, s[18:19]
	s_waitcnt vmcnt(6)
	s_barrier
	v_mfma_f32_16x16x32_f16 v[52:55], v[198:201], v[166:169], v[52:55]
	v_mfma_f32_16x16x32_f16 v[48:51], v[206:209], v[166:169], v[48:51]
	v_mfma_f32_16x16x32_f16 v[36:39], v[198:201], v[174:177], v[36:39]
	v_mfma_f32_16x16x32_f16 v[32:35], v[206:209], v[174:177], v[32:35]
	v_mfma_f32_16x16x32_f16 v[20:23], v[198:201], v[182:185], v[20:23]
	v_mfma_f32_16x16x32_f16 v[16:19], v[206:209], v[182:185], v[16:19]
	v_mfma_f32_16x16x32_f16 v[4:7], v[198:201], v[190:193], v[4:7]
	v_mfma_f32_16x16x32_f16 v[0:3], v[206:209], v[190:193], v[0:3]
	v_mfma_f32_16x16x32_f16 v[52:55], v[202:205], v[170:173], v[52:55]
	v_mfma_f32_16x16x32_f16 v[48:51], v[210:213], v[170:173], v[48:51]
	v_mfma_f32_16x16x32_f16 v[36:39], v[202:205], v[178:181], v[36:39]
	v_mfma_f32_16x16x32_f16 v[32:35], v[210:213], v[178:181], v[32:35]
	v_mfma_f32_16x16x32_f16 v[20:23], v[202:205], v[186:189], v[20:23]
	v_mfma_f32_16x16x32_f16 v[16:19], v[210:213], v[186:189], v[16:19]
	v_mfma_f32_16x16x32_f16 v[4:7], v[202:205], v[194:197], v[4:7]
	v_mfma_f32_16x16x32_f16 v[0:3], v[210:213], v[194:197], v[0:3]
	s_barrier
	s_add_i32 s78, s78, 2
	s_add_u32 s16, s16, 0x100
	s_addc_u32 s17, s17, 0
	s_add_u32 s76, s76, 0x100
	s_addc_u32 s77, s77, 0
	s_cmp_gt_u32 s78, 29
	s_cbranch_scc0 .LBB0_197
	s_setprio 0
	v_readlane_b32 s52, v254, 21
	v_readlane_b32 s54, v254, 23
	v_readlane_b32 s55, v254, 24
	v_lshl_add_u32 v154, s14, 8, v148
	v_lshl_or_b32 v144, s4, 8, v150
	v_mov_b64_e32 v[146:147], s[54:55]
	v_mad_i64_i32 v[146:147], s[4:5], v154, s70, v[146:147]
	v_cmp_gt_i32_e32 vcc, s71, v144
	v_ashrrev_i32_e32 v145, 31, v144
	v_readlane_b32 s53, v254, 22
	v_readlane_b32 s56, v254, 25
	v_readlane_b32 s57, v254, 26
	v_readlane_b32 s58, v254, 27
	v_readlane_b32 s59, v254, 28
	v_readlane_b32 s60, v254, 29
	v_readlane_b32 s61, v254, 30
	v_readlane_b32 s62, v254, 31
	v_readlane_b32 s63, v254, 32
	v_readlane_b32 s64, v254, 33
	v_readlane_b32 s65, v254, 34
	v_readlane_b32 s66, v254, 35
	v_readlane_b32 s67, v254, 36
	s_and_saveexec_b64 s[4:5], vcc
	s_cbranch_execz .LBB0_200
	v_cvt_pk_f16_f32 v123, v122, v123
	v_cvt_pk_f16_f32 v122, v120, v121
	v_cvt_pk_f16_f32 v121, v126, v127
	v_cvt_pk_f16_f32 v120, v124, v125
	v_lshl_add_u64 v[124:125], v[144:145], 1, v[146:147]
	global_store_dwordx4 v[124:125], v[120:123], off

.Lprio_y1:
.LBB0_647:
	ds_read_b128 v[80:83], v243
	ds_read_b128 v[88:91], v243 offset:1024
	ds_read_b128 v[96:99], v243 offset:2048
	ds_read_b128 v[100:103], v243 offset:3072
	s_add_i32 m0, s15, 0xc000
	ds_read_b128 v[120:123], v244
	ds_read_b128 v[132:135], v244 offset:1024
	ds_read_b128 v[136:139], v244 offset:2048
	ds_read_b128 v[148:151], v244 offset:3072
	ds_read_b128 v[152:155], v244 offset:4096
	ds_read_b128 v[156:159], v244 offset:5120
	ds_read_b128 v[160:163], v244 offset:6144
	ds_read_b128 v[172:175], v244 offset:7168
	global_load_lds_dwordx4 v212, s[16:17]
	s_add_i32 m0, s15, 0xe000
	s_nop 0
	global_load_lds_dwordx4 v214, s[16:17]
	s_waitcnt lgkmcnt(8)
	s_barrier
	s_waitcnt lgkmcnt(0)
	v_mfma_f32_16x16x32_f16 v[168:171], v[80:83], v[120:123], v[168:171]
	v_mfma_f32_16x16x32_f16 v[164:167], v[96:99], v[120:123], v[164:167]
	v_mfma_f32_16x16x32_f16 v[128:131], v[80:83], v[136:139], v[128:131]
	v_mfma_f32_16x16x32_f16 v[124:127], v[96:99], v[136:139], v[124:127]
	v_mfma_f32_16x16x32_f16 v[108:111], v[80:83], v[152:155], v[108:111]
	v_mfma_f32_16x16x32_f16 v[104:107], v[96:99], v[152:155], v[104:107]
	v_mfma_f32_16x16x32_f16 v[76:79], v[80:83], v[160:163], v[76:79]
	v_mfma_f32_16x16x32_f16 v[72:75], v[96:99], v[160:163], v[72:75]
	v_mfma_f32_16x16x32_f16 v[168:171], v[88:91], v[132:135], v[168:171]
	v_mfma_f32_16x16x32_f16 v[164:167], v[100:103], v[132:135], v[164:167]
	v_mfma_f32_16x16x32_f16 v[128:131], v[88:91], v[148:151], v[128:131]
	v_mfma_f32_16x16x32_f16 v[124:127], v[100:103], v[148:151], v[124:127]
	v_mfma_f32_16x16x32_f16 v[108:111], v[88:91], v[156:159], v[108:111]
	v_mfma_f32_16x16x32_f16 v[104:107], v[100:103], v[156:159], v[104:107]
	v_mfma_f32_16x16x32_f16 v[76:79], v[88:91], v[172:175], v[76:79]
	v_mfma_f32_16x16x32_f16 v[72:75], v[100:103], v[172:175], v[72:75]
	s_barrier
	s_add_u32 s18, s16, 0xfff80080
	s_addc_u32 s19, s17, -1
	s_cmp_eq_u32 s80, 28
	s_cselect_b32 s21, s9, s19
	s_cselect_b32 s20, s31, s18
	s_cselect_b32 s19, s7, s79
	s_cselect_b32 s18, s77, s78
	s_add_i32 s81, s71, s24
	s_add_u32 s72, s18, s4
	s_addc_u32 s73, s19, s5
	s_mov_b32 m0, s81
	ds_read_b128 v[176:179], v245
	ds_read_b128 v[180:183], v245 offset:1024
	ds_read_b128 v[184:187], v245 offset:2048
	ds_read_b128 v[188:191], v245 offset:3072
	global_load_lds_dwordx4 v206, s[18:19]
	s_add_i32 m0, s81, 0x2000
	s_nop 0
	global_load_lds_dwordx4 v210, s[18:19]
	s_barrier
	s_waitcnt lgkmcnt(0)
	v_mfma_f32_16x16x32_f16 v[144:147], v[176:179], v[120:123], v[144:147]
	v_mfma_f32_16x16x32_f16 v[116:119], v[176:179], v[136:139], v[116:119]
	v_mfma_f32_16x16x32_f16 v[112:115], v[184:187], v[136:139], v[112:115]
	v_mfma_f32_16x16x32_f16 v[92:95], v[176:179], v[152:155], v[92:95]
	v_mfma_f32_16x16x32_f16 v[84:87], v[184:187], v[152:155], v[84:87]
	v_mfma_f32_16x16x32_f16 v[68:71], v[176:179], v[160:163], v[68:71]
	v_mfma_f32_16x16x32_f16 v[64:67], v[184:187], v[160:163], v[64:67]
	v_mfma_f32_16x16x32_f16 v[144:147], v[180:183], v[132:135], v[144:147]
	v_mfma_f32_16x16x32_f16 v[120:123], v[184:187], v[120:123], v[140:143]
	v_mfma_f32_16x16x32_f16 v[116:119], v[180:183], v[148:151], v[116:119]
	v_mfma_f32_16x16x32_f16 v[112:115], v[188:191], v[148:151], v[112:115]
	v_mfma_f32_16x16x32_f16 v[92:95], v[180:183], v[156:159], v[92:95]
	v_mfma_f32_16x16x32_f16 v[84:87], v[188:191], v[156:159], v[84:87]
	v_mfma_f32_16x16x32_f16 v[68:71], v[180:183], v[172:175], v[68:71]
	v_mfma_f32_16x16x32_f16 v[64:67], v[188:191], v[172:175], v[64:67]
	v_mfma_f32_16x16x32_f16 v[120:123], v[188:191], v[132:135], v[120:123]
	s_barrier
	s_mov_b32 m0, s15
	s_add_u32 s74, s20, s4
	s_addc_u32 s75, s21, s5
	ds_read_b128 v[132:135], v244 offset:16384
	ds_read_b128 v[136:139], v244 offset:17408
	ds_read_b128 v[140:143], v244 offset:18432
	ds_read_b128 v[148:151], v244 offset:19456
	ds_read_b128 v[152:155], v244 offset:20480
	ds_read_b128 v[156:159], v244 offset:21504
	ds_read_b128 v[160:163], v244 offset:22528
	ds_read_b128 v[172:175], v244 offset:23552
	global_load_lds_dwordx4 v204, s[20:21]
	s_mov_b32 m0, s25
	s_nop 0
	global_load_lds_dwordx4 v208, s[20:21]
	s_barrier
	s_waitcnt lgkmcnt(0)
	v_mfma_f32_16x16x32_f16 v[60:63], v[80:83], v[132:135], v[60:63]
	v_mfma_f32_16x16x32_f16 v[56:59], v[96:99], v[132:135], v[56:59]
	v_mfma_f32_16x16x32_f16 v[44:47], v[80:83], v[140:143], v[44:47]
	v_mfma_f32_16x16x32_f16 v[40:43], v[96:99], v[140:143], v[40:43]
	v_mfma_f32_16x16x32_f16 v[28:31], v[80:83], v[152:155], v[28:31]
	v_mfma_f32_16x16x32_f16 v[24:27], v[96:99], v[152:155], v[24:27]
	v_mfma_f32_16x16x32_f16 v[12:15], v[80:83], v[160:163], v[12:15]
	v_mfma_f32_16x16x32_f16 v[8:11], v[96:99], v[160:163], v[8:11]
	v_mfma_f32_16x16x32_f16 v[60:63], v[88:91], v[136:139], v[60:63]
	v_mfma_f32_16x16x32_f16 v[56:59], v[100:103], v[136:139], v[56:59]
	v_mfma_f32_16x16x32_f16 v[44:47], v[88:91], v[148:151], v[44:47]
	v_mfma_f32_16x16x32_f16 v[40:43], v[100:103], v[148:151], v[40:43]
	v_mfma_f32_16x16x32_f16 v[28:31], v[88:91], v[156:159], v[28:31]
	v_mfma_f32_16x16x32_f16 v[24:27], v[100:103], v[156:159], v[24:27]
	v_mfma_f32_16x16x32_f16 v[12:15], v[88:91], v[172:175], v[12:15]
	v_mfma_f32_16x16x32_f16 v[8:11], v[100:103], v[172:175], v[8:11]
	s_barrier
	s_add_u32 s82, s18, 0x80000
	s_addc_u32 s83, s19, 0
	s_add_i32 s81, s76, s24
	s_mov_b32 m0, s81
	s_nop 0
	global_load_lds_dwordx4 v206, s[82:83]
	s_add_i32 m0, s81, 0x2000
	s_nop 0
	global_load_lds_dwordx4 v210, s[82:83]
	s_waitcnt vmcnt(6)
	s_barrier
	v_mfma_f32_16x16x32_f16 v[52:55], v[176:179], v[132:135], v[52:55]
	v_mfma_f32_16x16x32_f16 v[48:51], v[184:187], v[132:135], v[48:51]
	v_mfma_f32_16x16x32_f16 v[36:39], v[176:179], v[140:143], v[36:39]
	v_mfma_f32_16x16x32_f16 v[32:35], v[184:187], v[140:143], v[32:35]
	v_mfma_f32_16x16x32_f16 v[20:23], v[176:179], v[152:155], v[20:23]
	v_mfma_f32_16x16x32_f16 v[16:19], v[184:187], v[152:155], v[16:19]
	v_mfma_f32_16x16x32_f16 v[4:7], v[176:179], v[160:163], v[4:7]
	v_mfma_f32_16x16x32_f16 v[0:3], v[184:187], v[160:163], v[0:3]
	v_mfma_f32_16x16x32_f16 v[52:55], v[180:183], v[136:139], v[52:55]
	v_mfma_f32_16x16x32_f16 v[48:51], v[188:191], v[136:139], v[48:51]
	v_mfma_f32_16x16x32_f16 v[36:39], v[180:183], v[148:151], v[36:39]
	v_mfma_f32_16x16x32_f16 v[32:35], v[188:191], v[148:151], v[32:35]
	v_mfma_f32_16x16x32_f16 v[20:23], v[180:183], v[156:159], v[20:23]
	v_mfma_f32_16x16x32_f16 v[16:19], v[188:191], v[156:159], v[16:19]
	v_mfma_f32_16x16x32_f16 v[4:7], v[180:183], v[172:175], v[4:7]
	v_mfma_f32_16x16x32_f16 v[0:3], v[188:191], v[172:175], v[0:3]
	s_barrier
	s_add_i32 s81, 0, 0x18000
	v_add_u32_e32 v100, s81, v241
	ds_read_b128 v[80:83], v100
	ds_read_b128 v[88:91], v100 offset:1024
	ds_read_b128 v[96:99], v100 offset:2048
	ds_read_b128 v[100:103], v100 offset:3072
	s_add_u32 s20, s20, 0x80000
	s_addc_u32 s21, s21, 0
	s_mov_b32 m0, s26
	ds_read_b128 v[132:135], v244 offset:32768
	ds_read_b128 v[136:139], v244 offset:33792
	ds_read_b128 v[148:151], v244 offset:34816
	ds_read_b128 v[152:155], v244 offset:35840
	ds_read_b128 v[156:159], v244 offset:36864
	ds_read_b128 v[160:163], v244 offset:37888
	ds_read_b128 v[172:175], v244 offset:38912
	ds_read_b128 v[176:179], v244 offset:39936
	global_load_lds_dwordx4 v204, s[20:21]
	s_mov_b32 m0, s27
	s_nop 0
	global_load_lds_dwordx4 v208, s[20:21]
	s_waitcnt lgkmcnt(8)
	s_barrier
	s_waitcnt lgkmcnt(0)
	v_mfma_f32_16x16x32_f16 v[140:143], v[80:83], v[132:135], v[168:171]
	v_mfma_f32_16x16x32_f16 v[168:171], v[88:91], v[136:139], v[140:143]
	v_mfma_f32_16x16x32_f16 v[140:143], v[96:99], v[132:135], v[164:167]
	v_mfma_f32_16x16x32_f16 v[128:131], v[80:83], v[148:151], v[128:131]
	v_mfma_f32_16x16x32_f16 v[124:127], v[96:99], v[148:151], v[124:127]
	v_mfma_f32_16x16x32_f16 v[108:111], v[80:83], v[156:159], v[108:111]
	v_mfma_f32_16x16x32_f16 v[104:107], v[96:99], v[156:159], v[104:107]
	v_mfma_f32_16x16x32_f16 v[76:79], v[80:83], v[172:175], v[76:79]
	v_mfma_f32_16x16x32_f16 v[72:75], v[96:99], v[172:175], v[72:75]
	v_mfma_f32_16x16x32_f16 v[164:167], v[100:103], v[136:139], v[140:143]
	v_mfma_f32_16x16x32_f16 v[128:131], v[88:91], v[152:155], v[128:131]
	v_mfma_f32_16x16x32_f16 v[124:127], v[100:103], v[152:155], v[124:127]
	v_mfma_f32_16x16x32_f16 v[108:111], v[88:91], v[160:163], v[108:111]
	v_mfma_f32_16x16x32_f16 v[104:107], v[100:103], v[160:163], v[104:107]
	v_mfma_f32_16x16x32_f16 v[76:79], v[88:91], v[176:179], v[76:79]
	v_mfma_f32_16x16x32_f16 v[72:75], v[100:103], v[176:179], v[72:75]
	s_barrier
	s_add_i32 s20, 0, 0x1c000
	v_add_u32_e32 v140, s20, v241
	s_add_i32 s21, s81, s24
	ds_read_b128 v[180:183], v140
	ds_read_b128 v[184:187], v140 offset:1024
	ds_read_b128 v[188:191], v140 offset:2048
	ds_read_b128 v[192:195], v140 offset:3072
	s_mov_b32 m0, s21
	s_nop 0
	global_load_lds_dwordx4 v206, s[72:73]
	s_add_i32 m0, s21, 0x2000
	s_nop 0
	global_load_lds_dwordx4 v210, s[72:73]
	s_barrier
	s_waitcnt lgkmcnt(0)
	v_mfma_f32_16x16x32_f16 v[140:143], v[180:183], v[132:135], v[144:147]
	v_mfma_f32_16x16x32_f16 v[120:123], v[188:191], v[132:135], v[120:123]
	v_mfma_f32_16x16x32_f16 v[116:119], v[180:183], v[148:151], v[116:119]
	v_mfma_f32_16x16x32_f16 v[112:115], v[188:191], v[148:151], v[112:115]
	v_mfma_f32_16x16x32_f16 v[92:95], v[180:183], v[156:159], v[92:95]
	v_mfma_f32_16x16x32_f16 v[84:87], v[188:191], v[156:159], v[84:87]
	v_mfma_f32_16x16x32_f16 v[68:71], v[180:183], v[172:175], v[68:71]
	v_mfma_f32_16x16x32_f16 v[64:67], v[188:191], v[172:175], v[64:67]
	v_mfma_f32_16x16x32_f16 v[144:147], v[184:187], v[136:139], v[140:143]
	v_mfma_f32_16x16x32_f16 v[140:143], v[192:195], v[136:139], v[120:123]
	v_mfma_f32_16x16x32_f16 v[116:119], v[184:187], v[152:155], v[116:119]
	v_mfma_f32_16x16x32_f16 v[112:115], v[192:195], v[152:155], v[112:115]
	v_mfma_f32_16x16x32_f16 v[92:95], v[184:187], v[160:163], v[92:95]
	v_mfma_f32_16x16x32_f16 v[84:87], v[192:195], v[160:163], v[84:87]
	v_mfma_f32_16x16x32_f16 v[68:71], v[184:187], v[176:179], v[68:71]
	v_mfma_f32_16x16x32_f16 v[64:67], v[192:195], v[176:179], v[64:67]
	s_barrier
	s_mov_b32 m0, s35
	ds_read_b128 v[120:123], v244 offset:49152
	ds_read_b128 v[132:135], v244 offset:50176
	ds_read_b128 v[136:139], v244 offset:51200
	ds_read_b128 v[148:151], v244 offset:52224
	ds_read_b128 v[152:155], v244 offset:53248
	ds_read_b128 v[156:159], v244 offset:54272
	ds_read_b128 v[160:163], v244 offset:55296
	ds_read_b128 v[172:175], v244 offset:56320
	global_load_lds_dwordx4 v204, s[74:75]
	s_mov_b32 m0, s68
	s_nop 0
	global_load_lds_dwordx4 v208, s[74:75]
	s_barrier
	s_waitcnt lgkmcnt(0)
	v_mfma_f32_16x16x32_f16 v[60:63], v[80:83], v[120:123], v[60:63]
	v_mfma_f32_16x16x32_f16 v[56:59], v[96:99], v[120:123], v[56:59]
	v_mfma_f32_16x16x32_f16 v[44:47], v[80:83], v[136:139], v[44:47]
	v_mfma_f32_16x16x32_f16 v[40:43], v[96:99], v[136:139], v[40:43]
	v_mfma_f32_16x16x32_f16 v[28:31], v[80:83], v[152:155], v[28:31]
	v_mfma_f32_16x16x32_f16 v[24:27], v[96:99], v[152:155], v[24:27]
	v_mfma_f32_16x16x32_f16 v[12:15], v[80:83], v[160:163], v[12:15]
	v_mfma_f32_16x16x32_f16 v[8:11], v[96:99], v[160:163], v[8:11]
	v_mfma_f32_16x16x32_f16 v[60:63], v[88:91], v[132:135], v[60:63]
	v_mfma_f32_16x16x32_f16 v[56:59], v[100:103], v[132:135], v[56:59]
	v_mfma_f32_16x16x32_f16 v[44:47], v[88:91], v[148:151], v[44:47]
	v_mfma_f32_16x16x32_f16 v[40:43], v[100:103], v[148:151], v[40:43]
	v_mfma_f32_16x16x32_f16 v[28:31], v[88:91], v[156:159], v[28:31]
	v_mfma_f32_16x16x32_f16 v[24:27], v[100:103], v[156:159], v[24:27]
	v_mfma_f32_16x16x32_f16 v[12:15], v[88:91], v[172:175], v[12:15]
	v_mfma_f32_16x16x32_f16 v[8:11], v[100:103], v[172:175], v[8:11]
	s_barrier
	s_add_u32 s18, s18, 0x80080
	s_addc_u32 s19, s19, 0
	s_add_i32 s20, s20, s24
	s_mov_b32 m0, s20
	s_nop 0
	global_load_lds_dwordx4 v206, s[18:19]
	s_add_i32 m0, s20, 0x2000
	s_nop 0
	global_load_lds_dwordx4 v210, s[18:19]
	s_waitcnt vmcnt(6)
	s_barrier
	v_mfma_f32_16x16x32_f16 v[52:55], v[180:183], v[120:123], v[52:55]
	v_mfma_f32_16x16x32_f16 v[48:51], v[188:191], v[120:123], v[48:51]
	v_mfma_f32_16x16x32_f16 v[36:39], v[180:183], v[136:139], v[36:39]
	v_mfma_f32_16x16x32_f16 v[32:35], v[188:191], v[136:139], v[32:35]
	v_mfma_f32_16x16x32_f16 v[20:23], v[180:183], v[152:155], v[20:23]
	v_mfma_f32_16x16x32_f16 v[16:19], v[188:191], v[152:155], v[16:19]
	v_mfma_f32_16x16x32_f16 v[4:7], v[180:183], v[160:163], v[4:7]
	v_mfma_f32_16x16x32_f16 v[0:3], v[188:191], v[160:163], v[0:3]
	v_mfma_f32_16x16x32_f16 v[52:55], v[184:187], v[132:135], v[52:55]
	v_mfma_f32_16x16x32_f16 v[48:51], v[192:195], v[132:135], v[48:51]
	v_mfma_f32_16x16x32_f16 v[36:39], v[184:187], v[148:151], v[36:39]
	v_mfma_f32_16x16x32_f16 v[32:35], v[192:195], v[148:151], v[32:35]
	v_mfma_f32_16x16x32_f16 v[20:23], v[184:187], v[156:159], v[20:23]
	v_mfma_f32_16x16x32_f16 v[16:19], v[192:195], v[156:159], v[16:19]
	v_mfma_f32_16x16x32_f16 v[4:7], v[184:187], v[172:175], v[4:7]
	v_mfma_f32_16x16x32_f16 v[0:3], v[192:195], v[172:175], v[0:3]
	s_barrier
	s_add_i32 s80, s80, 2
	s_add_u32 s16, s16, 0x100
	s_addc_u32 s17, s17, 0
	s_add_u32 s78, s78, 0x100
	s_addc_u32 s79, s79, 0
	s_cmp_gt_u32 s80, 29
	s_cbranch_scc0 .LBB0_647
	s_setprio 0
	s_lshl_b32 s7, s14, 8
	s_add_i32 s9, s7, 0xffffe000
	s_lshr_b32 s9, s9, 11
	s_mulk_i32 s9, 0x1800
	s_addk_i32 s9, 0x1800
	s_cmp_gt_i32 s14, 31
	s_cselect_b32 s16, s9, 0
	s_ashr_i32 s17, s16, 31
	v_lshl_or_b32 v120, s30, 8, v242
	s_lshl_b64 s[16:17], s[16:17], 2
	s_add_u32 s16, s29, s16
	v_ashrrev_i32_e32 v121, 31, v120
	v_add_u32_e32 v122, s7, v240
	s_addc_u32 s17, s34, s17
	v_lshlrev_b64 v[220:221], 1, v[120:121]
	v_ashrrev_i32_e32 v123, 31, v122
	v_lshl_add_u64 v[88:89], v[120:121], 2, s[16:17]
	v_lshl_add_u64 v[120:121], s[40:41], 0, v[220:221]
	v_lshlrev_b64 v[236:237], 12, v[122:123]
	v_lshl_add_u64 v[132:133], v[120:121], 0, v[236:237]
	global_load_dwordx4 v[96:99], v[88:89], off offset:16
	global_load_dwordx4 v[100:103], v[88:89], off
	global_load_dwordx4 v[80:83], v[88:89], off offset:528
	s_nop 0
	global_load_dwordx4 v[88:91], v[88:89], off offset:512
	s_nop 0
	global_load_dwordx4 v[246:249], v[132:133], off nt
	global_load_dwordx4 v[200:203], v[132:133], off offset:256 nt
	v_or_b32_e32 v132, 16, v122
	v_ashrrev_i32_e32 v133, 31, v132
	v_lshlrev_b64 v[234:235], 12, v[132:133]
	v_lshl_add_u64 v[132:133], v[120:121], 0, v[234:235]
	global_load_dwordx4 v[196:199], v[132:133], off nt
	global_load_dwordx4 v[192:195], v[132:133], off offset:256 nt
	v_or_b32_e32 v132, 32, v122
	v_ashrrev_i32_e32 v133, 31, v132
	v_lshlrev_b64 v[232:233], 12, v[132:133]
	v_lshl_add_u64 v[132:133], v[120:121], 0, v[232:233]
	global_load_dwordx4 v[188:191], v[132:133], off nt
	global_load_dwordx4 v[184:187], v[132:133], off offset:256 nt
	v_or_b32_e32 v122, 48, v122
	v_ashrrev_i32_e32 v123, 31, v122
	v_lshlrev_b64 v[230:231], 12, v[122:123]
	v_lshl_add_u64 v[122:123], v[120:121], 0, v[230:231]
	global_load_dwordx4 v[180:183], v[122:123], off nt
	global_load_dwordx4 v[176:179], v[122:123], off offset:256 nt
	s_mov_b64 s[16:17], 0x80000
	v_lshl_add_u64 v[228:229], v[236:237], 0, s[16:17]
	v_lshl_add_u64 v[122:123], v[120:121], 0, v[228:229]
	global_load_dwordx4 v[172:175], v[122:123], off nt
	global_load_dwordx4 v[160:163], v[122:123], off offset:256 nt
	s_mov_b64 s[16:17], 0x90000
	v_lshl_add_u64 v[226:227], v[236:237], 0, s[16:17]
	v_lshl_add_u64 v[122:123], v[120:121], 0, v[226:227]
	global_load_dwordx4 v[156:159], v[122:123], off nt
	global_load_dwordx4 v[152:155], v[122:123], off offset:256 nt
	s_mov_b64 s[16:17], 0xa0000
	v_lshl_add_u64 v[224:225], v[236:237], 0, s[16:17]
	v_lshl_add_u64 v[122:123], v[120:121], 0, v[224:225]
	global_load_dwordx4 v[148:151], v[122:123], off nt
	global_load_dwordx4 v[136:139], v[122:123], off offset:256 nt
	s_mov_b64 s[16:17], 0xb0000
	v_lshl_add_u64 v[222:223], v[236:237], 0, s[16:17]
	v_lshl_add_u64 v[120:121], v[120:121], 0, v[222:223]
	global_load_dwordx4 v[132:135], v[120:121], off nt
	s_nop 0
	global_load_dwordx4 v[120:123], v[120:121], off offset:256 nt
	s_and_b64 vcc, exec, s[2:3]
	s_mov_b32 s30, s6
	s_mov_b32 s14, s8
	s_mov_b64 s[18:19], s[12:13]
	s_mov_b64 s[16:17], s[10:11]
	s_waitcnt vmcnt(0)
	v_cvt_f32_f16_e32 v250, v246
	v_cvt_f32_f16_sdwa v251, v246 dst_sel:DWORD dst_unused:UNUSED_PAD src0_sel:WORD_1
	v_pk_fma_f32 v[168:169], v[168:169], v[100:101], v[250:251]
	s_nop 0
	v_cvt_pk_f16_f32 v246, v168, v169
	v_cvt_f32_f16_e32 v168, v248
	v_cvt_f32_f16_sdwa v169, v248 dst_sel:DWORD dst_unused:UNUSED_PAD src0_sel:WORD_1
	v_pk_fma_f32 v[164:165], v[164:165], v[96:97], v[168:169]
	s_nop 0
	v_cvt_pk_f16_f32 v248, v164, v165
	v_cvt_f32_f16_e32 v164, v247
	v_cvt_f32_f16_sdwa v165, v247 dst_sel:DWORD dst_unused:UNUSED_PAD src0_sel:WORD_1
	v_pk_fma_f32 v[164:165], v[170:171], v[102:103], v[164:165]
	s_nop 0
	v_cvt_pk_f16_f32 v247, v164, v165
	v_cvt_f32_f16_e32 v164, v249
	v_cvt_f32_f16_sdwa v165, v249 dst_sel:DWORD dst_unused:UNUSED_PAD src0_sel:WORD_1
	v_pk_fma_f32 v[164:165], v[166:167], v[98:99], v[164:165]
	s_nop 0
	v_cvt_pk_f16_f32 v249, v164, v165
	v_lshl_add_u64 v[164:165], s[0:1], 0, v[236:237]
	v_lshl_add_u64 v[168:169], v[164:165], 0, v[220:221]
	v_cvt_f32_f16_e32 v164, v200
	v_cvt_f32_f16_sdwa v165, v200 dst_sel:DWORD dst_unused:UNUSED_PAD src0_sel:WORD_1
	global_store_dwordx4 v[168:169], v[246:249], off
	v_pk_fma_f32 v[144:145], v[144:145], v[88:89], v[164:165]
	s_nop 0
	v_cvt_pk_f16_f32 v164, v144, v145
	v_cvt_f32_f16_e32 v144, v202
	v_cvt_f32_f16_sdwa v145, v202 dst_sel:DWORD dst_unused:UNUSED_PAD src0_sel:WORD_1
	v_pk_fma_f32 v[140:141], v[140:141], v[80:81], v[144:145]
	s_nop 0
	v_cvt_pk_f16_f32 v166, v140, v141
	v_cvt_f32_f16_e32 v140, v201
	v_cvt_f32_f16_sdwa v141, v201 dst_sel:DWORD dst_unused:UNUSED_PAD src0_sel:WORD_1
	v_pk_fma_f32 v[140:141], v[146:147], v[90:91], v[140:141]
	s_nop 0
	v_cvt_pk_f16_f32 v165, v140, v141
	v_cvt_f32_f16_e32 v140, v203
	v_cvt_f32_f16_sdwa v141, v203 dst_sel:DWORD dst_unused:UNUSED_PAD src0_sel:WORD_1
	v_pk_fma_f32 v[140:141], v[142:143], v[82:83], v[140:141]
	s_nop 0
	v_cvt_pk_f16_f32 v167, v140, v141
	v_cvt_f32_f16_e32 v140, v196
	v_cvt_f32_f16_sdwa v141, v196 dst_sel:DWORD dst_unused:UNUSED_PAD src0_sel:WORD_1
	global_store_dwordx4 v[168:169], v[164:167], off offset:256
	v_pk_fma_f32 v[128:129], v[128:129], v[100:101], v[140:141]
	s_nop 0
	v_cvt_pk_f16_f32 v140, v128, v129
	v_cvt_f32_f16_e32 v128, v198
	v_cvt_f32_f16_sdwa v129, v198 dst_sel:DWORD dst_unused:UNUSED_PAD src0_sel:WORD_1
	v_pk_fma_f32 v[124:125], v[124:125], v[96:97], v[128:129]
	s_nop 0
	v_cvt_pk_f16_f32 v142, v124, v125
	v_cvt_f32_f16_e32 v124, v197
	v_cvt_f32_f16_sdwa v125, v197 dst_sel:DWORD dst_unused:UNUSED_PAD src0_sel:WORD_1
	v_pk_fma_f32 v[124:125], v[130:131], v[102:103], v[124:125]
	s_nop 0
	v_cvt_pk_f16_f32 v141, v124, v125
	v_cvt_f32_f16_e32 v124, v199
	v_cvt_f32_f16_sdwa v125, v199 dst_sel:DWORD dst_unused:UNUSED_PAD src0_sel:WORD_1
	v_pk_fma_f32 v[124:125], v[126:127], v[98:99], v[124:125]
	s_nop 0
	v_cvt_pk_f16_f32 v143, v124, v125
	v_lshl_add_u64 v[124:125], s[0:1], 0, v[234:235]
	v_lshl_add_u64 v[128:129], v[124:125], 0, v[220:221]
	v_cvt_f32_f16_e32 v124, v192
	v_cvt_f32_f16_sdwa v125, v192 dst_sel:DWORD dst_unused:UNUSED_PAD src0_sel:WORD_1
	global_store_dwordx4 v[128:129], v[140:143], off
	v_pk_fma_f32 v[116:117], v[116:117], v[88:89], v[124:125]
	s_nop 0
	v_cvt_pk_f16_f32 v124, v116, v117
	v_cvt_f32_f16_e32 v116, v194
	v_cvt_f32_f16_sdwa v117, v194 dst_sel:DWORD dst_unused:UNUSED_PAD src0_sel:WORD_1
	v_pk_fma_f32 v[112:113], v[112:113], v[80:81], v[116:117]
	s_nop 0
	v_cvt_pk_f16_f32 v126, v112, v113
	v_cvt_f32_f16_e32 v112, v193
	v_cvt_f32_f16_sdwa v113, v193 dst_sel:DWORD dst_unused:UNUSED_PAD src0_sel:WORD_1
	v_pk_fma_f32 v[112:113], v[118:119], v[90:91], v[112:113]
	s_nop 0
	v_cvt_pk_f16_f32 v125, v112, v113
	v_cvt_f32_f16_e32 v112, v195
	v_cvt_f32_f16_sdwa v113, v195 dst_sel:DWORD dst_unused:UNUSED_PAD src0_sel:WORD_1
	v_pk_fma_f32 v[112:113], v[114:115], v[82:83], v[112:113]
	s_nop 0
	v_cvt_pk_f16_f32 v127, v112, v113
	v_cvt_f32_f16_e32 v112, v188
	v_cvt_f32_f16_sdwa v113, v188 dst_sel:DWORD dst_unused:UNUSED_PAD src0_sel:WORD_1
	global_store_dwordx4 v[128:129], v[124:127], off offset:256
	v_pk_fma_f32 v[108:109], v[108:109], v[100:101], v[112:113]
	s_nop 0
	v_cvt_pk_f16_f32 v112, v108, v109
	v_cvt_f32_f16_e32 v108, v190
	v_cvt_f32_f16_sdwa v109, v190 dst_sel:DWORD dst_unused:UNUSED_PAD src0_sel:WORD_1
	v_pk_fma_f32 v[104:105], v[104:105], v[96:97], v[108:109]
	s_nop 0
	v_cvt_pk_f16_f32 v114, v104, v105
	v_cvt_f32_f16_e32 v104, v189
	v_cvt_f32_f16_sdwa v105, v189 dst_sel:DWORD dst_unused:UNUSED_PAD src0_sel:WORD_1
	v_pk_fma_f32 v[104:105], v[110:111], v[102:103], v[104:105]
	s_nop 0
	v_cvt_pk_f16_f32 v113, v104, v105
	v_cvt_f32_f16_e32 v104, v191
	v_cvt_f32_f16_sdwa v105, v191 dst_sel:DWORD dst_unused:UNUSED_PAD src0_sel:WORD_1
	v_pk_fma_f32 v[104:105], v[106:107], v[98:99], v[104:105]
	s_nop 0
	v_cvt_pk_f16_f32 v115, v104, v105
	v_lshl_add_u64 v[104:105], s[0:1], 0, v[232:233]
	v_lshl_add_u64 v[108:109], v[104:105], 0, v[220:221]
	v_cvt_f32_f16_e32 v104, v184
	v_cvt_f32_f16_sdwa v105, v184 dst_sel:DWORD dst_unused:UNUSED_PAD src0_sel:WORD_1
	global_store_dwordx4 v[108:109], v[112:115], off
	v_pk_fma_f32 v[92:93], v[92:93], v[88:89], v[104:105]
	s_nop 0
	v_cvt_pk_f16_f32 v104, v92, v93
	v_cvt_f32_f16_e32 v92, v186
	v_cvt_f32_f16_sdwa v93, v186 dst_sel:DWORD dst_unused:UNUSED_PAD src0_sel:WORD_1
	v_pk_fma_f32 v[84:85], v[84:85], v[80:81], v[92:93]
	s_nop 0
	v_cvt_pk_f16_f32 v106, v84, v85
	v_cvt_f32_f16_e32 v84, v185
	v_cvt_f32_f16_sdwa v85, v185 dst_sel:DWORD dst_unused:UNUSED_PAD src0_sel:WORD_1
	v_pk_fma_f32 v[84:85], v[94:95], v[90:91], v[84:85]
	s_nop 0
	v_cvt_pk_f16_f32 v105, v84, v85
	v_cvt_f32_f16_e32 v84, v187
	v_cvt_f32_f16_sdwa v85, v187 dst_sel:DWORD dst_unused:UNUSED_PAD src0_sel:WORD_1
	v_pk_fma_f32 v[84:85], v[86:87], v[82:83], v[84:85]
	s_nop 0
	v_cvt_pk_f16_f32 v107, v84, v85
	v_cvt_f32_f16_e32 v84, v180
	v_cvt_f32_f16_sdwa v85, v180 dst_sel:DWORD dst_unused:UNUSED_PAD src0_sel:WORD_1
	global_store_dwordx4 v[108:109], v[104:107], off offset:256
	v_pk_fma_f32 v[76:77], v[76:77], v[100:101], v[84:85]
	s_nop 0
	v_cvt_pk_f16_f32 v84, v76, v77
	v_cvt_f32_f16_e32 v76, v182
	v_cvt_f32_f16_sdwa v77, v182 dst_sel:DWORD dst_unused:UNUSED_PAD src0_sel:WORD_1
	v_pk_fma_f32 v[72:73], v[72:73], v[96:97], v[76:77]
	s_nop 0
	v_cvt_pk_f16_f32 v86, v72, v73
	v_cvt_f32_f16_e32 v72, v181
	v_cvt_f32_f16_sdwa v73, v181 dst_sel:DWORD dst_unused:UNUSED_PAD src0_sel:WORD_1
	v_pk_fma_f32 v[72:73], v[78:79], v[102:103], v[72:73]
	s_nop 0
	v_cvt_pk_f16_f32 v85, v72, v73
	v_cvt_f32_f16_e32 v72, v183
	v_cvt_f32_f16_sdwa v73, v183 dst_sel:DWORD dst_unused:UNUSED_PAD src0_sel:WORD_1
	v_pk_fma_f32 v[72:73], v[74:75], v[98:99], v[72:73]
	s_nop 0
	v_cvt_pk_f16_f32 v87, v72, v73
	v_lshl_add_u64 v[72:73], s[0:1], 0, v[230:231]
	v_lshl_add_u64 v[76:77], v[72:73], 0, v[220:221]
	v_cvt_f32_f16_e32 v72, v176
	v_cvt_f32_f16_sdwa v73, v176 dst_sel:DWORD dst_unused:UNUSED_PAD src0_sel:WORD_1
	global_store_dwordx4 v[76:77], v[84:87], off
	v_pk_fma_f32 v[68:69], v[68:69], v[88:89], v[72:73]
	s_nop 0
	v_cvt_pk_f16_f32 v72, v68, v69
	v_cvt_f32_f16_e32 v68, v178
	v_cvt_f32_f16_sdwa v69, v178 dst_sel:DWORD dst_unused:UNUSED_PAD src0_sel:WORD_1
	v_pk_fma_f32 v[64:65], v[64:65], v[80:81], v[68:69]
	s_nop 0
	v_cvt_pk_f16_f32 v74, v64, v65
	v_cvt_f32_f16_e32 v64, v177
	v_cvt_f32_f16_sdwa v65, v177 dst_sel:DWORD dst_unused:UNUSED_PAD src0_sel:WORD_1
	v_pk_fma_f32 v[64:65], v[70:71], v[90:91], v[64:65]
	s_nop 0
	v_cvt_pk_f16_f32 v73, v64, v65
	v_cvt_f32_f16_e32 v64, v179
	v_cvt_f32_f16_sdwa v65, v179 dst_sel:DWORD dst_unused:UNUSED_PAD src0_sel:WORD_1
	v_pk_fma_f32 v[64:65], v[66:67], v[82:83], v[64:65]
	s_nop 0
	v_cvt_pk_f16_f32 v75, v64, v65
	v_cvt_f32_f16_e32 v64, v172
	v_cvt_f32_f16_sdwa v65, v172 dst_sel:DWORD dst_unused:UNUSED_PAD src0_sel:WORD_1
	global_store_dwordx4 v[76:77], v[72:75], off offset:256
	v_pk_fma_f32 v[60:61], v[60:61], v[100:101], v[64:65]
	s_nop 0
	v_cvt_pk_f16_f32 v64, v60, v61
	v_cvt_f32_f16_e32 v60, v174
	v_cvt_f32_f16_sdwa v61, v174 dst_sel:DWORD dst_unused:UNUSED_PAD src0_sel:WORD_1
	v_pk_fma_f32 v[56:57], v[56:57], v[96:97], v[60:61]
	s_nop 0
	v_cvt_pk_f16_f32 v66, v56, v57
	v_cvt_f32_f16_e32 v56, v173
	v_cvt_f32_f16_sdwa v57, v173 dst_sel:DWORD dst_unused:UNUSED_PAD src0_sel:WORD_1
	v_pk_fma_f32 v[56:57], v[62:63], v[102:103], v[56:57]
	s_nop 0
	v_cvt_pk_f16_f32 v65, v56, v57
	v_cvt_f32_f16_e32 v56, v175
	v_cvt_f32_f16_sdwa v57, v175 dst_sel:DWORD dst_unused:UNUSED_PAD src0_sel:WORD_1
	v_pk_fma_f32 v[56:57], v[58:59], v[98:99], v[56:57]
	s_nop 0
	v_cvt_pk_f16_f32 v67, v56, v57
	v_lshl_add_u64 v[56:57], s[0:1], 0, v[228:229]
	v_lshl_add_u64 v[60:61], v[56:57], 0, v[220:221]
	v_cvt_f32_f16_e32 v56, v160
	v_cvt_f32_f16_sdwa v57, v160 dst_sel:DWORD dst_unused:UNUSED_PAD src0_sel:WORD_1
	global_store_dwordx4 v[60:61], v[64:67], off
	v_pk_fma_f32 v[52:53], v[52:53], v[88:89], v[56:57]
	s_nop 0
	v_cvt_pk_f16_f32 v56, v52, v53
	v_cvt_f32_f16_e32 v52, v162
	v_cvt_f32_f16_sdwa v53, v162 dst_sel:DWORD dst_unused:UNUSED_PAD src0_sel:WORD_1
	v_pk_fma_f32 v[48:49], v[48:49], v[80:81], v[52:53]
	s_nop 0
	v_cvt_pk_f16_f32 v58, v48, v49
	v_cvt_f32_f16_e32 v48, v161
	v_cvt_f32_f16_sdwa v49, v161 dst_sel:DWORD dst_unused:UNUSED_PAD src0_sel:WORD_1
	v_pk_fma_f32 v[48:49], v[54:55], v[90:91], v[48:49]
	s_nop 0
	v_cvt_pk_f16_f32 v57, v48, v49
	v_cvt_f32_f16_e32 v48, v163
	v_cvt_f32_f16_sdwa v49, v163 dst_sel:DWORD dst_unused:UNUSED_PAD src0_sel:WORD_1
	v_pk_fma_f32 v[48:49], v[50:51], v[82:83], v[48:49]
	s_nop 0
	v_cvt_pk_f16_f32 v59, v48, v49
	v_cvt_f32_f16_e32 v48, v156
	v_cvt_f32_f16_sdwa v49, v156 dst_sel:DWORD dst_unused:UNUSED_PAD src0_sel:WORD_1
	global_store_dwordx4 v[60:61], v[56:59], off offset:256
	v_pk_fma_f32 v[44:45], v[44:45], v[100:101], v[48:49]
	s_nop 0
	v_cvt_pk_f16_f32 v48, v44, v45
	v_cvt_f32_f16_e32 v44, v158
	v_cvt_f32_f16_sdwa v45, v158 dst_sel:DWORD dst_unused:UNUSED_PAD src0_sel:WORD_1
	v_pk_fma_f32 v[40:41], v[40:41], v[96:97], v[44:45]
	s_nop 0
	v_cvt_pk_f16_f32 v50, v40, v41
	v_cvt_f32_f16_e32 v40, v157
	v_cvt_f32_f16_sdwa v41, v157 dst_sel:DWORD dst_unused:UNUSED_PAD src0_sel:WORD_1
	v_pk_fma_f32 v[40:41], v[46:47], v[102:103], v[40:41]
	s_nop 0
	v_cvt_pk_f16_f32 v49, v40, v41
	v_cvt_f32_f16_e32 v40, v159
	v_cvt_f32_f16_sdwa v41, v159 dst_sel:DWORD dst_unused:UNUSED_PAD src0_sel:WORD_1
	v_pk_fma_f32 v[40:41], v[42:43], v[98:99], v[40:41]
	s_nop 0
	v_cvt_pk_f16_f32 v51, v40, v41
	v_lshl_add_u64 v[40:41], s[0:1], 0, v[226:227]
	v_lshl_add_u64 v[44:45], v[40:41], 0, v[220:221]
	v_cvt_f32_f16_e32 v40, v152
	v_cvt_f32_f16_sdwa v41, v152 dst_sel:DWORD dst_unused:UNUSED_PAD src0_sel:WORD_1
	global_store_dwordx4 v[44:45], v[48:51], off
	v_pk_fma_f32 v[36:37], v[36:37], v[88:89], v[40:41]
	s_nop 0
	v_cvt_pk_f16_f32 v40, v36, v37
	v_cvt_f32_f16_e32 v36, v154
	v_cvt_f32_f16_sdwa v37, v154 dst_sel:DWORD dst_unused:UNUSED_PAD src0_sel:WORD_1
	v_pk_fma_f32 v[32:33], v[32:33], v[80:81], v[36:37]
	s_nop 0
	v_cvt_pk_f16_f32 v42, v32, v33
	v_cvt_f32_f16_e32 v32, v153
	v_cvt_f32_f16_sdwa v33, v153 dst_sel:DWORD dst_unused:UNUSED_PAD src0_sel:WORD_1
	v_pk_fma_f32 v[32:33], v[38:39], v[90:91], v[32:33]
	s_nop 0
	v_cvt_pk_f16_f32 v41, v32, v33
	v_cvt_f32_f16_e32 v32, v155
	v_cvt_f32_f16_sdwa v33, v155 dst_sel:DWORD dst_unused:UNUSED_PAD src0_sel:WORD_1
	v_pk_fma_f32 v[32:33], v[34:35], v[82:83], v[32:33]
	s_nop 0
	v_cvt_pk_f16_f32 v43, v32, v33
	v_cvt_f32_f16_e32 v32, v148
	v_cvt_f32_f16_sdwa v33, v148 dst_sel:DWORD dst_unused:UNUSED_PAD src0_sel:WORD_1
	global_store_dwordx4 v[44:45], v[40:43], off offset:256
	v_pk_fma_f32 v[28:29], v[28:29], v[100:101], v[32:33]
	s_nop 0
	v_cvt_pk_f16_f32 v32, v28, v29
	v_cvt_f32_f16_e32 v28, v150
	v_cvt_f32_f16_sdwa v29, v150 dst_sel:DWORD dst_unused:UNUSED_PAD src0_sel:WORD_1
	v_pk_fma_f32 v[24:25], v[24:25], v[96:97], v[28:29]
	s_nop 0
	v_cvt_pk_f16_f32 v34, v24, v25
	v_cvt_f32_f16_e32 v24, v149
	v_cvt_f32_f16_sdwa v25, v149 dst_sel:DWORD dst_unused:UNUSED_PAD src0_sel:WORD_1
	v_pk_fma_f32 v[24:25], v[30:31], v[102:103], v[24:25]
	s_nop 0
	v_cvt_pk_f16_f32 v33, v24, v25
	v_cvt_f32_f16_e32 v24, v151
	v_cvt_f32_f16_sdwa v25, v151 dst_sel:DWORD dst_unused:UNUSED_PAD src0_sel:WORD_1
	v_pk_fma_f32 v[24:25], v[26:27], v[98:99], v[24:25]
	s_nop 0
	v_cvt_pk_f16_f32 v35, v24, v25
	v_lshl_add_u64 v[24:25], s[0:1], 0, v[224:225]
	v_lshl_add_u64 v[28:29], v[24:25], 0, v[220:221]
	v_cvt_f32_f16_e32 v24, v136
	v_cvt_f32_f16_sdwa v25, v136 dst_sel:DWORD dst_unused:UNUSED_PAD src0_sel:WORD_1
	global_store_dwordx4 v[28:29], v[32:35], off
	v_pk_fma_f32 v[20:21], v[20:21], v[88:89], v[24:25]
	s_nop 0
	v_cvt_pk_f16_f32 v24, v20, v21
	v_cvt_f32_f16_e32 v20, v138
	v_cvt_f32_f16_sdwa v21, v138 dst_sel:DWORD dst_unused:UNUSED_PAD src0_sel:WORD_1
	v_pk_fma_f32 v[16:17], v[16:17], v[80:81], v[20:21]
	s_nop 0
	v_cvt_pk_f16_f32 v26, v16, v17
	v_cvt_f32_f16_e32 v16, v137
	v_cvt_f32_f16_sdwa v17, v137 dst_sel:DWORD dst_unused:UNUSED_PAD src0_sel:WORD_1
	v_pk_fma_f32 v[16:17], v[22:23], v[90:91], v[16:17]
	s_nop 0
	v_cvt_pk_f16_f32 v25, v16, v17
	v_cvt_f32_f16_e32 v16, v139
	v_cvt_f32_f16_sdwa v17, v139 dst_sel:DWORD dst_unused:UNUSED_PAD src0_sel:WORD_1
	v_pk_fma_f32 v[16:17], v[18:19], v[82:83], v[16:17]
	s_nop 0
	v_cvt_pk_f16_f32 v27, v16, v17
	v_cvt_f32_f16_e32 v16, v132
	v_cvt_f32_f16_sdwa v17, v132 dst_sel:DWORD dst_unused:UNUSED_PAD src0_sel:WORD_1
	global_store_dwordx4 v[28:29], v[24:27], off offset:256
	v_pk_fma_f32 v[12:13], v[12:13], v[100:101], v[16:17]
	s_nop 0
	v_cvt_pk_f16_f32 v16, v12, v13
	v_cvt_f32_f16_e32 v12, v134
	v_cvt_f32_f16_sdwa v13, v134 dst_sel:DWORD dst_unused:UNUSED_PAD src0_sel:WORD_1
	v_pk_fma_f32 v[8:9], v[8:9], v[96:97], v[12:13]
	s_nop 0
	v_cvt_pk_f16_f32 v18, v8, v9
	v_cvt_f32_f16_e32 v8, v133
	v_cvt_f32_f16_sdwa v9, v133 dst_sel:DWORD dst_unused:UNUSED_PAD src0_sel:WORD_1
	v_pk_fma_f32 v[8:9], v[14:15], v[102:103], v[8:9]
	s_nop 0
	v_cvt_pk_f16_f32 v17, v8, v9
	v_cvt_f32_f16_e32 v8, v135
	v_cvt_f32_f16_sdwa v9, v135 dst_sel:DWORD dst_unused:UNUSED_PAD src0_sel:WORD_1
	v_pk_fma_f32 v[8:9], v[10:11], v[98:99], v[8:9]
	s_nop 0
	v_cvt_pk_f16_f32 v19, v8, v9
	v_lshl_add_u64 v[8:9], s[0:1], 0, v[222:223]
	v_lshl_add_u64 v[12:13], v[8:9], 0, v[220:221]
	v_cvt_f32_f16_e32 v8, v120
	v_cvt_f32_f16_sdwa v9, v120 dst_sel:DWORD dst_unused:UNUSED_PAD src0_sel:WORD_1
	global_store_dwordx4 v[12:13], v[16:19], off
	v_pk_fma_f32 v[4:5], v[4:5], v[88:89], v[8:9]
	s_nop 0
	v_cvt_pk_f16_f32 v8, v4, v5
	v_cvt_f32_f16_e32 v4, v122
	v_cvt_f32_f16_sdwa v5, v122 dst_sel:DWORD dst_unused:UNUSED_PAD src0_sel:WORD_1
	v_pk_fma_f32 v[0:1], v[0:1], v[80:81], v[4:5]
	s_nop 0
	v_cvt_pk_f16_f32 v10, v0, v1
	v_cvt_f32_f16_e32 v0, v121
	v_cvt_f32_f16_sdwa v1, v121 dst_sel:DWORD dst_unused:UNUSED_PAD src0_sel:WORD_1
	v_pk_fma_f32 v[0:1], v[6:7], v[90:91], v[0:1]
	s_nop 0
	v_cvt_pk_f16_f32 v9, v0, v1
	v_cvt_f32_f16_e32 v0, v123
	v_cvt_f32_f16_sdwa v1, v123 dst_sel:DWORD dst_unused:UNUSED_PAD src0_sel:WORD_1
	v_pk_fma_f32 v[0:1], v[2:3], v[82:83], v[0:1]
	s_nop 0
	v_cvt_pk_f16_f32 v11, v0, v1
	global_store_dwordx4 v[12:13], v[8:11], off offset:256
	s_cbranch_vccz .LBB0_640
	s_waitcnt vmcnt(0)
	s_cmpk_gt_u32 s22, 0xff
	s_cbranch_scc1 .LBB0_651
	s_barrier

.Lprio_y3:
.LBB0_1185:
	ds_read_b128 v[88:91], v243
	ds_read_b128 v[96:99], v243 offset:1024
	ds_read_b128 v[108:111], v243 offset:2048
	ds_read_b128 v[116:119], v243 offset:3072
	s_add_i32 m0, s23, 0xc000
	ds_read_b128 v[128:131], v244
	ds_read_b128 v[136:139], v244 offset:1024
	ds_read_b128 v[144:147], v244 offset:2048
	ds_read_b128 v[148:151], v244 offset:3072
	ds_read_b128 v[152:155], v244 offset:4096
	ds_read_b128 v[164:167], v244 offset:5120
	ds_read_b128 v[168:171], v244 offset:6144
	ds_read_b128 v[172:175], v244 offset:7168
	global_load_lds_dwordx4 v212, s[24:25]
	s_add_i32 m0, s23, 0xe000
	s_nop 0
	global_load_lds_dwordx4 v214, s[24:25]
	s_waitcnt lgkmcnt(8)
	s_barrier
	s_waitcnt lgkmcnt(0)
	v_mfma_f32_16x16x32_f16 v[160:163], v[88:91], v[128:131], v[160:163]
	v_mfma_f32_16x16x32_f16 v[156:159], v[108:111], v[128:131], v[156:159]
	v_mfma_f32_16x16x32_f16 v[124:127], v[88:91], v[144:147], v[124:127]
	v_mfma_f32_16x16x32_f16 v[120:123], v[108:111], v[144:147], v[120:123]
	v_mfma_f32_16x16x32_f16 v[100:103], v[88:91], v[152:155], v[100:103]
	v_mfma_f32_16x16x32_f16 v[92:95], v[108:111], v[152:155], v[92:95]
	v_mfma_f32_16x16x32_f16 v[76:79], v[88:91], v[168:171], v[76:79]
	v_mfma_f32_16x16x32_f16 v[72:75], v[108:111], v[168:171], v[72:75]
	v_mfma_f32_16x16x32_f16 v[160:163], v[96:99], v[136:139], v[160:163]
	v_mfma_f32_16x16x32_f16 v[156:159], v[116:119], v[136:139], v[156:159]
	v_mfma_f32_16x16x32_f16 v[124:127], v[96:99], v[148:151], v[124:127]
	v_mfma_f32_16x16x32_f16 v[120:123], v[116:119], v[148:151], v[120:123]
	v_mfma_f32_16x16x32_f16 v[100:103], v[96:99], v[164:167], v[100:103]
	v_mfma_f32_16x16x32_f16 v[92:95], v[116:119], v[164:167], v[92:95]
	v_mfma_f32_16x16x32_f16 v[76:79], v[96:99], v[172:175], v[76:79]
	v_mfma_f32_16x16x32_f16 v[72:75], v[116:119], v[172:175], v[72:75]
	s_barrier
	s_add_u32 s26, s24, 0xfff80080
	s_addc_u32 s27, s25, -1
	s_cmp_eq_u32 s64, 28
	s_cselect_b32 s29, s17, s27
	s_cselect_b32 s28, s31, s26
	s_cselect_b32 s27, s15, s63
	s_cselect_b32 s26, s61, s62
	s_add_i32 s65, s59, s44
	s_add_u32 s72, s26, s6
	s_addc_u32 s73, s27, s7
	s_mov_b32 m0, s65
	ds_read_b128 v[176:179], v245
	ds_read_b128 v[180:183], v245 offset:1024
	ds_read_b128 v[184:187], v245 offset:2048
	ds_read_b128 v[188:191], v245 offset:3072
	global_load_lds_dwordx4 v206, s[26:27]
	s_add_i32 m0, s65, 0x2000
	s_nop 0
	global_load_lds_dwordx4 v210, s[26:27]
	s_barrier
	s_waitcnt lgkmcnt(0)
	v_mfma_f32_16x16x32_f16 v[140:143], v[176:179], v[128:131], v[140:143]
	v_mfma_f32_16x16x32_f16 v[112:115], v[176:179], v[144:147], v[112:115]
	v_mfma_f32_16x16x32_f16 v[104:107], v[184:187], v[144:147], v[104:107]
	v_mfma_f32_16x16x32_f16 v[84:87], v[176:179], v[152:155], v[84:87]
	v_mfma_f32_16x16x32_f16 v[80:83], v[184:187], v[152:155], v[80:83]
	v_mfma_f32_16x16x32_f16 v[68:71], v[176:179], v[168:171], v[68:71]
	v_mfma_f32_16x16x32_f16 v[64:67], v[184:187], v[168:171], v[64:67]
	v_mfma_f32_16x16x32_f16 v[140:143], v[180:183], v[136:139], v[140:143]
	v_mfma_f32_16x16x32_f16 v[128:131], v[184:187], v[128:131], v[132:135]
	v_mfma_f32_16x16x32_f16 v[112:115], v[180:183], v[148:151], v[112:115]
	v_mfma_f32_16x16x32_f16 v[104:107], v[188:191], v[148:151], v[104:107]
	v_mfma_f32_16x16x32_f16 v[84:87], v[180:183], v[164:167], v[84:87]
	v_mfma_f32_16x16x32_f16 v[80:83], v[188:191], v[164:167], v[80:83]
	v_mfma_f32_16x16x32_f16 v[68:71], v[180:183], v[172:175], v[68:71]
	v_mfma_f32_16x16x32_f16 v[64:67], v[188:191], v[172:175], v[64:67]
	v_mfma_f32_16x16x32_f16 v[128:131], v[188:191], v[136:139], v[128:131]
	s_barrier
	s_mov_b32 m0, s23
	s_add_u32 s74, s28, s6
	s_addc_u32 s75, s29, s7
	ds_read_b128 v[132:135], v244 offset:16384
	ds_read_b128 v[136:139], v244 offset:17408
	ds_read_b128 v[144:147], v244 offset:18432
	ds_read_b128 v[148:151], v244 offset:19456
	ds_read_b128 v[152:155], v244 offset:20480
	ds_read_b128 v[164:167], v244 offset:21504
	ds_read_b128 v[168:171], v244 offset:22528
	ds_read_b128 v[172:175], v244 offset:23552
	global_load_lds_dwordx4 v204, s[28:29]
	s_mov_b32 m0, s45
	s_nop 0
	global_load_lds_dwordx4 v208, s[28:29]
	s_barrier
	s_waitcnt lgkmcnt(0)
	v_mfma_f32_16x16x32_f16 v[60:63], v[88:91], v[132:135], v[60:63]
	v_mfma_f32_16x16x32_f16 v[56:59], v[108:111], v[132:135], v[56:59]
	v_mfma_f32_16x16x32_f16 v[44:47], v[88:91], v[144:147], v[44:47]
	v_mfma_f32_16x16x32_f16 v[40:43], v[108:111], v[144:147], v[40:43]
	v_mfma_f32_16x16x32_f16 v[28:31], v[88:91], v[152:155], v[28:31]
	v_mfma_f32_16x16x32_f16 v[24:27], v[108:111], v[152:155], v[24:27]
	v_mfma_f32_16x16x32_f16 v[12:15], v[88:91], v[168:171], v[12:15]
	v_mfma_f32_16x16x32_f16 v[8:11], v[108:111], v[168:171], v[8:11]
	v_mfma_f32_16x16x32_f16 v[60:63], v[96:99], v[136:139], v[60:63]
	v_mfma_f32_16x16x32_f16 v[56:59], v[116:119], v[136:139], v[56:59]
	v_mfma_f32_16x16x32_f16 v[44:47], v[96:99], v[148:151], v[44:47]
	v_mfma_f32_16x16x32_f16 v[40:43], v[116:119], v[148:151], v[40:43]
	v_mfma_f32_16x16x32_f16 v[28:31], v[96:99], v[164:167], v[28:31]
	v_mfma_f32_16x16x32_f16 v[24:27], v[116:119], v[164:167], v[24:27]
	v_mfma_f32_16x16x32_f16 v[12:15], v[96:99], v[172:175], v[12:15]
	v_mfma_f32_16x16x32_f16 v[8:11], v[116:119], v[172:175], v[8:11]
	s_barrier
	s_add_u32 s66, s26, 0x80000
	s_addc_u32 s67, s27, 0
	s_add_i32 s65, s60, s44
	s_mov_b32 m0, s65
	s_nop 0
	global_load_lds_dwordx4 v206, s[66:67]
	s_add_i32 m0, s65, 0x2000
	s_nop 0
	global_load_lds_dwordx4 v210, s[66:67]
	s_waitcnt vmcnt(6)
	s_barrier
	v_mfma_f32_16x16x32_f16 v[52:55], v[176:179], v[132:135], v[52:55]
	v_mfma_f32_16x16x32_f16 v[48:51], v[184:187], v[132:135], v[48:51]
	v_mfma_f32_16x16x32_f16 v[36:39], v[176:179], v[144:147], v[36:39]
	v_mfma_f32_16x16x32_f16 v[32:35], v[184:187], v[144:147], v[32:35]
	v_mfma_f32_16x16x32_f16 v[20:23], v[176:179], v[152:155], v[20:23]
	v_mfma_f32_16x16x32_f16 v[16:19], v[184:187], v[152:155], v[16:19]
	v_mfma_f32_16x16x32_f16 v[4:7], v[176:179], v[168:171], v[4:7]
	v_mfma_f32_16x16x32_f16 v[0:3], v[184:187], v[168:171], v[0:3]
	v_mfma_f32_16x16x32_f16 v[52:55], v[180:183], v[136:139], v[52:55]
	v_mfma_f32_16x16x32_f16 v[48:51], v[188:191], v[136:139], v[48:51]
	v_mfma_f32_16x16x32_f16 v[36:39], v[180:183], v[148:151], v[36:39]
	v_mfma_f32_16x16x32_f16 v[32:35], v[188:191], v[148:151], v[32:35]
	v_mfma_f32_16x16x32_f16 v[20:23], v[180:183], v[164:167], v[20:23]
	v_mfma_f32_16x16x32_f16 v[16:19], v[188:191], v[164:167], v[16:19]
	v_mfma_f32_16x16x32_f16 v[4:7], v[180:183], v[172:175], v[4:7]
	v_mfma_f32_16x16x32_f16 v[0:3], v[188:191], v[172:175], v[0:3]
	s_barrier
	s_add_i32 s65, 0, 0x18000
	v_add_u32_e32 v116, s65, v241
	ds_read_b128 v[88:91], v116
	ds_read_b128 v[96:99], v116 offset:1024
	ds_read_b128 v[108:111], v116 offset:2048
	ds_read_b128 v[116:119], v116 offset:3072
	s_add_u32 s28, s28, 0x80000
	s_addc_u32 s29, s29, 0
	s_mov_b32 m0, s48
	ds_read_b128 v[132:135], v244 offset:32768
	ds_read_b128 v[136:139], v244 offset:33792
	ds_read_b128 v[144:147], v244 offset:34816
	ds_read_b128 v[148:151], v244 offset:35840
	ds_read_b128 v[152:155], v244 offset:36864
	ds_read_b128 v[164:167], v244 offset:37888
	ds_read_b128 v[168:171], v244 offset:38912
	ds_read_b128 v[172:175], v244 offset:39936
	global_load_lds_dwordx4 v204, s[28:29]
	s_mov_b32 m0, s49
	s_nop 0
	global_load_lds_dwordx4 v208, s[28:29]
	s_waitcnt lgkmcnt(8)
	s_barrier
	s_waitcnt lgkmcnt(0)
	v_mfma_f32_16x16x32_f16 v[160:163], v[88:91], v[132:135], v[160:163]
	v_mfma_f32_16x16x32_f16 v[156:159], v[108:111], v[132:135], v[156:159]
	v_mfma_f32_16x16x32_f16 v[124:127], v[88:91], v[144:147], v[124:127]
	v_mfma_f32_16x16x32_f16 v[120:123], v[108:111], v[144:147], v[120:123]
	v_mfma_f32_16x16x32_f16 v[100:103], v[88:91], v[152:155], v[100:103]
	v_mfma_f32_16x16x32_f16 v[92:95], v[108:111], v[152:155], v[92:95]
	v_mfma_f32_16x16x32_f16 v[76:79], v[88:91], v[168:171], v[76:79]
	v_mfma_f32_16x16x32_f16 v[72:75], v[108:111], v[168:171], v[72:75]
	v_mfma_f32_16x16x32_f16 v[160:163], v[96:99], v[136:139], v[160:163]
	v_mfma_f32_16x16x32_f16 v[156:159], v[116:119], v[136:139], v[156:159]
	v_mfma_f32_16x16x32_f16 v[124:127], v[96:99], v[148:151], v[124:127]
	v_mfma_f32_16x16x32_f16 v[120:123], v[116:119], v[148:151], v[120:123]
	v_mfma_f32_16x16x32_f16 v[100:103], v[96:99], v[164:167], v[100:103]
	v_mfma_f32_16x16x32_f16 v[92:95], v[116:119], v[164:167], v[92:95]
	v_mfma_f32_16x16x32_f16 v[76:79], v[96:99], v[172:175], v[76:79]
	v_mfma_f32_16x16x32_f16 v[72:75], v[116:119], v[172:175], v[72:75]
	s_barrier
	s_add_i32 s28, 0, 0x1c000
	s_add_i32 s29, s65, s44
	v_add_u32_e32 v188, s28, v241
	s_mov_b32 m0, s29
	ds_read_b128 v[176:179], v188
	ds_read_b128 v[180:183], v188 offset:1024
	ds_read_b128 v[184:187], v188 offset:2048
	ds_read_b128 v[188:191], v188 offset:3072
	global_load_lds_dwordx4 v206, s[72:73]
	s_add_i32 m0, s29, 0x2000
	s_nop 0
	global_load_lds_dwordx4 v210, s[72:73]
	s_barrier
	s_waitcnt lgkmcnt(0)
	v_mfma_f32_16x16x32_f16 v[140:143], v[176:179], v[132:135], v[140:143]
	v_mfma_f32_16x16x32_f16 v[128:131], v[184:187], v[132:135], v[128:131]
	v_mfma_f32_16x16x32_f16 v[112:115], v[176:179], v[144:147], v[112:115]
	v_mfma_f32_16x16x32_f16 v[104:107], v[184:187], v[144:147], v[104:107]
	v_mfma_f32_16x16x32_f16 v[84:87], v[176:179], v[152:155], v[84:87]
	v_mfma_f32_16x16x32_f16 v[80:83], v[184:187], v[152:155], v[80:83]
	v_mfma_f32_16x16x32_f16 v[68:71], v[176:179], v[168:171], v[68:71]
	v_mfma_f32_16x16x32_f16 v[64:67], v[184:187], v[168:171], v[64:67]
	v_mfma_f32_16x16x32_f16 v[140:143], v[180:183], v[136:139], v[140:143]
	v_mfma_f32_16x16x32_f16 v[132:135], v[188:191], v[136:139], v[128:131]
	v_mfma_f32_16x16x32_f16 v[112:115], v[180:183], v[148:151], v[112:115]
	v_mfma_f32_16x16x32_f16 v[104:107], v[188:191], v[148:151], v[104:107]
	v_mfma_f32_16x16x32_f16 v[84:87], v[180:183], v[164:167], v[84:87]
	v_mfma_f32_16x16x32_f16 v[80:83], v[188:191], v[164:167], v[80:83]
	v_mfma_f32_16x16x32_f16 v[68:71], v[180:183], v[172:175], v[68:71]
	v_mfma_f32_16x16x32_f16 v[64:67], v[188:191], v[172:175], v[64:67]
	s_barrier
	s_mov_b32 m0, s51
	ds_read_b128 v[128:131], v244 offset:49152
	ds_read_b128 v[136:139], v244 offset:50176
	ds_read_b128 v[144:147], v244 offset:51200
	ds_read_b128 v[148:151], v244 offset:52224
	ds_read_b128 v[152:155], v244 offset:53248
	ds_read_b128 v[164:167], v244 offset:54272
	ds_read_b128 v[168:171], v244 offset:55296
	ds_read_b128 v[172:175], v244 offset:56320
	global_load_lds_dwordx4 v204, s[74:75]
	s_mov_b32 m0, s54
	s_nop 0
	global_load_lds_dwordx4 v208, s[74:75]
	s_barrier
	s_waitcnt lgkmcnt(0)
	v_mfma_f32_16x16x32_f16 v[60:63], v[88:91], v[128:131], v[60:63]
	v_mfma_f32_16x16x32_f16 v[56:59], v[108:111], v[128:131], v[56:59]
	v_mfma_f32_16x16x32_f16 v[44:47], v[88:91], v[144:147], v[44:47]
	v_mfma_f32_16x16x32_f16 v[40:43], v[108:111], v[144:147], v[40:43]
	v_mfma_f32_16x16x32_f16 v[28:31], v[88:91], v[152:155], v[28:31]
	v_mfma_f32_16x16x32_f16 v[24:27], v[108:111], v[152:155], v[24:27]
	v_mfma_f32_16x16x32_f16 v[12:15], v[88:91], v[168:171], v[12:15]
	v_mfma_f32_16x16x32_f16 v[8:11], v[108:111], v[168:171], v[8:11]
	v_mfma_f32_16x16x32_f16 v[60:63], v[96:99], v[136:139], v[60:63]
	v_mfma_f32_16x16x32_f16 v[56:59], v[116:119], v[136:139], v[56:59]
	v_mfma_f32_16x16x32_f16 v[44:47], v[96:99], v[148:151], v[44:47]
	v_mfma_f32_16x16x32_f16 v[40:43], v[116:119], v[148:151], v[40:43]
	v_mfma_f32_16x16x32_f16 v[28:31], v[96:99], v[164:167], v[28:31]
	v_mfma_f32_16x16x32_f16 v[24:27], v[116:119], v[164:167], v[24:27]
	v_mfma_f32_16x16x32_f16 v[12:15], v[96:99], v[172:175], v[12:15]
	v_mfma_f32_16x16x32_f16 v[8:11], v[116:119], v[172:175], v[8:11]
	s_barrier
	s_add_u32 s26, s26, 0x80080
	s_addc_u32 s27, s27, 0
	s_add_i32 s28, s28, s44
	s_mov_b32 m0, s28
	s_nop 0
	global_load_lds_dwordx4 v206, s[26:27]
	s_add_i32 m0, s28, 0x2000
	s_nop 0
	global_load_lds_dwordx4 v210, s[26:27]
	s_waitcnt vmcnt(6)
	s_barrier
	v_mfma_f32_16x16x32_f16 v[52:55], v[176:179], v[128:131], v[52:55]
	v_mfma_f32_16x16x32_f16 v[48:51], v[184:187], v[128:131], v[48:51]
	v_mfma_f32_16x16x32_f16 v[36:39], v[176:179], v[144:147], v[36:39]
	v_mfma_f32_16x16x32_f16 v[32:35], v[184:187], v[144:147], v[32:35]
	v_mfma_f32_16x16x32_f16 v[20:23], v[176:179], v[152:155], v[20:23]
	v_mfma_f32_16x16x32_f16 v[16:19], v[184:187], v[152:155], v[16:19]
	v_mfma_f32_16x16x32_f16 v[4:7], v[176:179], v[168:171], v[4:7]
	v_mfma_f32_16x16x32_f16 v[0:3], v[184:187], v[168:171], v[0:3]
	v_mfma_f32_16x16x32_f16 v[52:55], v[180:183], v[136:139], v[52:55]
	v_mfma_f32_16x16x32_f16 v[48:51], v[188:191], v[136:139], v[48:51]
	v_mfma_f32_16x16x32_f16 v[36:39], v[180:183], v[148:151], v[36:39]
	v_mfma_f32_16x16x32_f16 v[32:35], v[188:191], v[148:151], v[32:35]
	v_mfma_f32_16x16x32_f16 v[20:23], v[180:183], v[164:167], v[20:23]
	v_mfma_f32_16x16x32_f16 v[16:19], v[188:191], v[164:167], v[16:19]
	v_mfma_f32_16x16x32_f16 v[4:7], v[180:183], v[172:175], v[4:7]
	v_mfma_f32_16x16x32_f16 v[0:3], v[188:191], v[172:175], v[0:3]
	s_barrier
	s_add_i32 s64, s64, 2
	s_add_u32 s24, s24, 0x100
	s_addc_u32 s25, s25, 0
	s_add_u32 s62, s62, 0x100
	s_addc_u32 s63, s63, 0
	s_cmp_gt_u32 s64, 29
	s_cbranch_scc0 .LBB0_1185
	s_setprio 0
	s_lshl_b32 s15, s22, 8
	s_add_i32 s17, s15, 0xffffe000
	s_lshr_b32 s17, s17, 11
	s_mulk_i32 s17, 0x1800
	s_addk_i32 s17, 0x1800
	s_cmp_gt_i32 s22, 31
	s_cselect_b32 s24, s17, 0
	s_ashr_i32 s25, s24, 31
	v_lshl_or_b32 v128, s30, 8, v242
	s_lshl_b64 s[24:25], s[24:25], 2
	s_add_u32 s24, s42, s24
	v_ashrrev_i32_e32 v129, 31, v128
	v_add_u32_e32 v130, s15, v240
	s_addc_u32 s25, s43, s25
	v_lshlrev_b64 v[220:221], 1, v[128:129]
	v_ashrrev_i32_e32 v131, 31, v130
	v_lshl_add_u64 v[96:97], v[128:129], 2, s[24:25]
	v_lshl_add_u64 v[128:129], s[4:5], 0, v[220:221]
	v_lshlrev_b64 v[236:237], 12, v[130:131]
	v_lshl_add_u64 v[136:137], v[128:129], 0, v[236:237]
	global_load_dwordx4 v[108:111], v[96:97], off offset:16
	global_load_dwordx4 v[116:119], v[96:97], off
	global_load_dwordx4 v[88:91], v[96:97], off offset:528
	s_nop 0
	global_load_dwordx4 v[96:99], v[96:97], off offset:512
	s_nop 0
	global_load_dwordx4 v[246:249], v[136:137], off nt
	global_load_dwordx4 v[200:203], v[136:137], off offset:256 nt
	v_or_b32_e32 v136, 16, v130
	v_ashrrev_i32_e32 v137, 31, v136
	v_lshlrev_b64 v[234:235], 12, v[136:137]
	v_lshl_add_u64 v[136:137], v[128:129], 0, v[234:235]
	global_load_dwordx4 v[196:199], v[136:137], off nt
	global_load_dwordx4 v[192:195], v[136:137], off offset:256 nt
	v_or_b32_e32 v136, 32, v130
	v_ashrrev_i32_e32 v137, 31, v136
	v_lshlrev_b64 v[232:233], 12, v[136:137]
	v_lshl_add_u64 v[136:137], v[128:129], 0, v[232:233]
	global_load_dwordx4 v[188:191], v[136:137], off nt
	global_load_dwordx4 v[184:187], v[136:137], off offset:256 nt
	v_readlane_b32 s64, v254, 21
	v_readlane_b32 s68, v254, 25
	v_readlane_b32 s69, v254, 26
	s_mov_b64 s[56:57], s[68:69]
	v_or_b32_e32 v130, 48, v130
	v_ashrrev_i32_e32 v131, 31, v130
	v_lshlrev_b64 v[230:231], 12, v[130:131]
	v_lshl_add_u64 v[130:131], v[128:129], 0, v[230:231]
	global_load_dwordx4 v[180:183], v[130:131], off nt
	global_load_dwordx4 v[176:179], v[130:131], off offset:256 nt
	v_lshl_add_u64 v[228:229], v[236:237], 0, s[0:1]
	v_lshl_add_u64 v[130:131], v[128:129], 0, v[228:229]
	global_load_dwordx4 v[172:175], v[130:131], off nt
	global_load_dwordx4 v[168:171], v[130:131], off offset:256 nt
	v_lshl_add_u64 v[226:227], v[236:237], 0, s[8:9]
	v_lshl_add_u64 v[130:131], v[128:129], 0, v[226:227]
	global_load_dwordx4 v[164:167], v[130:131], off nt
	global_load_dwordx4 v[152:155], v[130:131], off offset:256 nt
	v_lshl_add_u64 v[224:225], v[236:237], 0, s[10:11]
	v_lshl_add_u64 v[130:131], v[128:129], 0, v[224:225]
	global_load_dwordx4 v[148:151], v[130:131], off nt
	global_load_dwordx4 v[144:147], v[130:131], off offset:256 nt
	v_lshl_add_u64 v[222:223], v[236:237], 0, s[12:13]
	v_lshl_add_u64 v[128:129], v[128:129], 0, v[222:223]
	global_load_dwordx4 v[136:139], v[128:129], off nt
	s_nop 0
	global_load_dwordx4 v[128:131], v[128:129], off offset:256 nt
	s_and_b64 vcc, exec, s[2:3]
	s_mov_b32 s30, s14
	s_mov_b32 s22, s16
	s_mov_b64 s[26:27], s[20:21]
	s_mov_b64 s[24:25], s[18:19]
	v_readlane_b32 s65, v254, 22
	v_readlane_b32 s66, v254, 23
	v_readlane_b32 s67, v254, 24
	v_readlane_b32 s70, v254, 27
	v_readlane_b32 s71, v254, 28
	v_readlane_b32 s72, v254, 29
	v_readlane_b32 s73, v254, 30
	v_readlane_b32 s74, v254, 31
	v_readlane_b32 s75, v254, 32
	v_readlane_b32 s76, v254, 33
	v_readlane_b32 s77, v254, 34
	v_readlane_b32 s78, v254, 35
	v_readlane_b32 s79, v254, 36
	s_waitcnt vmcnt(0)
	v_cvt_f32_f16_e32 v250, v246
	v_cvt_f32_f16_sdwa v251, v246 dst_sel:DWORD dst_unused:UNUSED_PAD src0_sel:WORD_1
	v_pk_fma_f32 v[160:161], v[160:161], v[116:117], v[250:251]
	s_nop 0
	v_cvt_pk_f16_f32 v246, v160, v161
	v_cvt_f32_f16_e32 v160, v248
	v_cvt_f32_f16_sdwa v161, v248 dst_sel:DWORD dst_unused:UNUSED_PAD src0_sel:WORD_1
	v_pk_fma_f32 v[156:157], v[156:157], v[108:109], v[160:161]
	s_nop 0
	v_cvt_pk_f16_f32 v248, v156, v157
	v_cvt_f32_f16_e32 v156, v247
	v_cvt_f32_f16_sdwa v157, v247 dst_sel:DWORD dst_unused:UNUSED_PAD src0_sel:WORD_1
	v_pk_fma_f32 v[156:157], v[162:163], v[118:119], v[156:157]
	s_nop 0
	v_cvt_pk_f16_f32 v247, v156, v157
	v_cvt_f32_f16_e32 v156, v249
	v_cvt_f32_f16_sdwa v157, v249 dst_sel:DWORD dst_unused:UNUSED_PAD src0_sel:WORD_1
	v_pk_fma_f32 v[156:157], v[158:159], v[110:111], v[156:157]
	s_nop 0
	v_cvt_pk_f16_f32 v249, v156, v157
	v_lshl_add_u64 v[156:157], s[56:57], 0, v[236:237]
	v_lshl_add_u64 v[160:161], v[156:157], 0, v[220:221]
	v_cvt_f32_f16_e32 v156, v200
	v_cvt_f32_f16_sdwa v157, v200 dst_sel:DWORD dst_unused:UNUSED_PAD src0_sel:WORD_1
	global_store_dwordx4 v[160:161], v[246:249], off
	v_pk_fma_f32 v[140:141], v[140:141], v[96:97], v[156:157]
	s_nop 0
	v_cvt_pk_f16_f32 v156, v140, v141
	v_cvt_f32_f16_e32 v140, v202
	v_cvt_f32_f16_sdwa v141, v202 dst_sel:DWORD dst_unused:UNUSED_PAD src0_sel:WORD_1
	v_pk_fma_f32 v[132:133], v[132:133], v[88:89], v[140:141]
	s_nop 0
	v_cvt_pk_f16_f32 v158, v132, v133
	v_cvt_f32_f16_e32 v132, v201
	v_cvt_f32_f16_sdwa v133, v201 dst_sel:DWORD dst_unused:UNUSED_PAD src0_sel:WORD_1
	v_pk_fma_f32 v[132:133], v[142:143], v[98:99], v[132:133]
	s_nop 0
	v_cvt_pk_f16_f32 v157, v132, v133
	v_cvt_f32_f16_e32 v132, v203
	v_cvt_f32_f16_sdwa v133, v203 dst_sel:DWORD dst_unused:UNUSED_PAD src0_sel:WORD_1
	v_pk_fma_f32 v[132:133], v[134:135], v[90:91], v[132:133]
	s_nop 0
	v_cvt_pk_f16_f32 v159, v132, v133
	v_cvt_f32_f16_e32 v132, v196
	v_cvt_f32_f16_sdwa v133, v196 dst_sel:DWORD dst_unused:UNUSED_PAD src0_sel:WORD_1
	global_store_dwordx4 v[160:161], v[156:159], off offset:256
	v_pk_fma_f32 v[124:125], v[124:125], v[116:117], v[132:133]
	s_nop 0
	v_cvt_pk_f16_f32 v132, v124, v125
	v_cvt_f32_f16_e32 v124, v198
	v_cvt_f32_f16_sdwa v125, v198 dst_sel:DWORD dst_unused:UNUSED_PAD src0_sel:WORD_1
	v_pk_fma_f32 v[120:121], v[120:121], v[108:109], v[124:125]
	s_nop 0
	v_cvt_pk_f16_f32 v134, v120, v121
	v_cvt_f32_f16_e32 v120, v197
	v_cvt_f32_f16_sdwa v121, v197 dst_sel:DWORD dst_unused:UNUSED_PAD src0_sel:WORD_1
	v_pk_fma_f32 v[120:121], v[126:127], v[118:119], v[120:121]
	s_nop 0
	v_cvt_pk_f16_f32 v133, v120, v121
	v_cvt_f32_f16_e32 v120, v199
	v_cvt_f32_f16_sdwa v121, v199 dst_sel:DWORD dst_unused:UNUSED_PAD src0_sel:WORD_1
	v_pk_fma_f32 v[120:121], v[122:123], v[110:111], v[120:121]
	s_nop 0
	v_cvt_pk_f16_f32 v135, v120, v121
	v_lshl_add_u64 v[120:121], s[56:57], 0, v[234:235]
	v_lshl_add_u64 v[124:125], v[120:121], 0, v[220:221]
	v_cvt_f32_f16_e32 v120, v192
	v_cvt_f32_f16_sdwa v121, v192 dst_sel:DWORD dst_unused:UNUSED_PAD src0_sel:WORD_1
	global_store_dwordx4 v[124:125], v[132:135], off
	v_pk_fma_f32 v[112:113], v[112:113], v[96:97], v[120:121]
	s_nop 0
	v_cvt_pk_f16_f32 v120, v112, v113
	v_cvt_f32_f16_e32 v112, v194
	v_cvt_f32_f16_sdwa v113, v194 dst_sel:DWORD dst_unused:UNUSED_PAD src0_sel:WORD_1
	v_pk_fma_f32 v[104:105], v[104:105], v[88:89], v[112:113]
	s_nop 0
	v_cvt_pk_f16_f32 v122, v104, v105
	v_cvt_f32_f16_e32 v104, v193
	v_cvt_f32_f16_sdwa v105, v193 dst_sel:DWORD dst_unused:UNUSED_PAD src0_sel:WORD_1
	v_pk_fma_f32 v[104:105], v[114:115], v[98:99], v[104:105]
	s_nop 0
	v_cvt_pk_f16_f32 v121, v104, v105
	v_cvt_f32_f16_e32 v104, v195
	v_cvt_f32_f16_sdwa v105, v195 dst_sel:DWORD dst_unused:UNUSED_PAD src0_sel:WORD_1
	v_pk_fma_f32 v[104:105], v[106:107], v[90:91], v[104:105]
	s_nop 0
	v_cvt_pk_f16_f32 v123, v104, v105
	v_cvt_f32_f16_e32 v104, v188
	v_cvt_f32_f16_sdwa v105, v188 dst_sel:DWORD dst_unused:UNUSED_PAD src0_sel:WORD_1
	global_store_dwordx4 v[124:125], v[120:123], off offset:256
	v_pk_fma_f32 v[100:101], v[100:101], v[116:117], v[104:105]
	s_nop 0
	v_cvt_pk_f16_f32 v104, v100, v101
	v_cvt_f32_f16_e32 v100, v190
	v_cvt_f32_f16_sdwa v101, v190 dst_sel:DWORD dst_unused:UNUSED_PAD src0_sel:WORD_1
	v_pk_fma_f32 v[92:93], v[92:93], v[108:109], v[100:101]
	s_nop 0
	v_cvt_pk_f16_f32 v106, v92, v93
	v_cvt_f32_f16_e32 v92, v189
	v_cvt_f32_f16_sdwa v93, v189 dst_sel:DWORD dst_unused:UNUSED_PAD src0_sel:WORD_1
	v_pk_fma_f32 v[92:93], v[102:103], v[118:119], v[92:93]
	s_nop 0
	v_cvt_pk_f16_f32 v105, v92, v93
	v_cvt_f32_f16_e32 v92, v191
	v_cvt_f32_f16_sdwa v93, v191 dst_sel:DWORD dst_unused:UNUSED_PAD src0_sel:WORD_1
	v_pk_fma_f32 v[92:93], v[94:95], v[110:111], v[92:93]
	s_nop 0
	v_cvt_pk_f16_f32 v107, v92, v93
	v_lshl_add_u64 v[92:93], s[56:57], 0, v[232:233]
	v_lshl_add_u64 v[100:101], v[92:93], 0, v[220:221]
	v_cvt_f32_f16_e32 v92, v184
	v_cvt_f32_f16_sdwa v93, v184 dst_sel:DWORD dst_unused:UNUSED_PAD src0_sel:WORD_1
	global_store_dwordx4 v[100:101], v[104:107], off
	v_pk_fma_f32 v[84:85], v[84:85], v[96:97], v[92:93]
	s_nop 0
	v_cvt_pk_f16_f32 v92, v84, v85
	v_cvt_f32_f16_e32 v84, v186
	v_cvt_f32_f16_sdwa v85, v186 dst_sel:DWORD dst_unused:UNUSED_PAD src0_sel:WORD_1
	v_pk_fma_f32 v[80:81], v[80:81], v[88:89], v[84:85]
	s_nop 0
	v_cvt_pk_f16_f32 v94, v80, v81
	v_cvt_f32_f16_e32 v80, v185
	v_cvt_f32_f16_sdwa v81, v185 dst_sel:DWORD dst_unused:UNUSED_PAD src0_sel:WORD_1
	v_pk_fma_f32 v[80:81], v[86:87], v[98:99], v[80:81]
	s_nop 0
	v_cvt_pk_f16_f32 v93, v80, v81
	v_cvt_f32_f16_e32 v80, v187
	v_cvt_f32_f16_sdwa v81, v187 dst_sel:DWORD dst_unused:UNUSED_PAD src0_sel:WORD_1
	v_pk_fma_f32 v[80:81], v[82:83], v[90:91], v[80:81]
	s_nop 0
	v_cvt_pk_f16_f32 v95, v80, v81
	v_cvt_f32_f16_e32 v80, v180
	v_cvt_f32_f16_sdwa v81, v180 dst_sel:DWORD dst_unused:UNUSED_PAD src0_sel:WORD_1
	global_store_dwordx4 v[100:101], v[92:95], off offset:256
	v_pk_fma_f32 v[76:77], v[76:77], v[116:117], v[80:81]
	s_nop 0
	v_cvt_pk_f16_f32 v80, v76, v77
	v_cvt_f32_f16_e32 v76, v182
	v_cvt_f32_f16_sdwa v77, v182 dst_sel:DWORD dst_unused:UNUSED_PAD src0_sel:WORD_1
	v_pk_fma_f32 v[72:73], v[72:73], v[108:109], v[76:77]
	s_nop 0
	v_cvt_pk_f16_f32 v82, v72, v73
	v_cvt_f32_f16_e32 v72, v181
	v_cvt_f32_f16_sdwa v73, v181 dst_sel:DWORD dst_unused:UNUSED_PAD src0_sel:WORD_1
	v_pk_fma_f32 v[72:73], v[78:79], v[118:119], v[72:73]
	s_nop 0
	v_cvt_pk_f16_f32 v81, v72, v73
	v_cvt_f32_f16_e32 v72, v183
	v_cvt_f32_f16_sdwa v73, v183 dst_sel:DWORD dst_unused:UNUSED_PAD src0_sel:WORD_1
	v_pk_fma_f32 v[72:73], v[74:75], v[110:111], v[72:73]
	s_nop 0
	v_cvt_pk_f16_f32 v83, v72, v73
	v_lshl_add_u64 v[72:73], s[56:57], 0, v[230:231]
	v_lshl_add_u64 v[76:77], v[72:73], 0, v[220:221]
	v_cvt_f32_f16_e32 v72, v176
	v_cvt_f32_f16_sdwa v73, v176 dst_sel:DWORD dst_unused:UNUSED_PAD src0_sel:WORD_1
	global_store_dwordx4 v[76:77], v[80:83], off
	v_pk_fma_f32 v[68:69], v[68:69], v[96:97], v[72:73]
	s_nop 0
	v_cvt_pk_f16_f32 v72, v68, v69
	v_cvt_f32_f16_e32 v68, v178
	v_cvt_f32_f16_sdwa v69, v178 dst_sel:DWORD dst_unused:UNUSED_PAD src0_sel:WORD_1
	v_pk_fma_f32 v[64:65], v[64:65], v[88:89], v[68:69]
	s_nop 0
	v_cvt_pk_f16_f32 v74, v64, v65
	v_cvt_f32_f16_e32 v64, v177
	v_cvt_f32_f16_sdwa v65, v177 dst_sel:DWORD dst_unused:UNUSED_PAD src0_sel:WORD_1
	v_pk_fma_f32 v[64:65], v[70:71], v[98:99], v[64:65]
	s_nop 0
	v_cvt_pk_f16_f32 v73, v64, v65
	v_cvt_f32_f16_e32 v64, v179
	v_cvt_f32_f16_sdwa v65, v179 dst_sel:DWORD dst_unused:UNUSED_PAD src0_sel:WORD_1
	v_pk_fma_f32 v[64:65], v[66:67], v[90:91], v[64:65]
	s_nop 0
	v_cvt_pk_f16_f32 v75, v64, v65
	v_cvt_f32_f16_e32 v64, v172
	v_cvt_f32_f16_sdwa v65, v172 dst_sel:DWORD dst_unused:UNUSED_PAD src0_sel:WORD_1
	global_store_dwordx4 v[76:77], v[72:75], off offset:256
	v_pk_fma_f32 v[60:61], v[60:61], v[116:117], v[64:65]
	s_nop 0
	v_cvt_pk_f16_f32 v64, v60, v61
	v_cvt_f32_f16_e32 v60, v174
	v_cvt_f32_f16_sdwa v61, v174 dst_sel:DWORD dst_unused:UNUSED_PAD src0_sel:WORD_1
	v_pk_fma_f32 v[56:57], v[56:57], v[108:109], v[60:61]
	s_nop 0
	v_cvt_pk_f16_f32 v66, v56, v57
	v_cvt_f32_f16_e32 v56, v173
	v_cvt_f32_f16_sdwa v57, v173 dst_sel:DWORD dst_unused:UNUSED_PAD src0_sel:WORD_1
	v_pk_fma_f32 v[56:57], v[62:63], v[118:119], v[56:57]
	s_nop 0
	v_cvt_pk_f16_f32 v65, v56, v57
	v_cvt_f32_f16_e32 v56, v175
	v_cvt_f32_f16_sdwa v57, v175 dst_sel:DWORD dst_unused:UNUSED_PAD src0_sel:WORD_1
	v_pk_fma_f32 v[56:57], v[58:59], v[110:111], v[56:57]
	s_nop 0
	v_cvt_pk_f16_f32 v67, v56, v57
	v_lshl_add_u64 v[56:57], s[56:57], 0, v[228:229]
	v_lshl_add_u64 v[60:61], v[56:57], 0, v[220:221]
	v_cvt_f32_f16_e32 v56, v168
	v_cvt_f32_f16_sdwa v57, v168 dst_sel:DWORD dst_unused:UNUSED_PAD src0_sel:WORD_1
	global_store_dwordx4 v[60:61], v[64:67], off
	v_pk_fma_f32 v[52:53], v[52:53], v[96:97], v[56:57]
	s_nop 0
	v_cvt_pk_f16_f32 v56, v52, v53
	v_cvt_f32_f16_e32 v52, v170
	v_cvt_f32_f16_sdwa v53, v170 dst_sel:DWORD dst_unused:UNUSED_PAD src0_sel:WORD_1
	v_pk_fma_f32 v[48:49], v[48:49], v[88:89], v[52:53]
	s_nop 0
	v_cvt_pk_f16_f32 v58, v48, v49
	v_cvt_f32_f16_e32 v48, v169
	v_cvt_f32_f16_sdwa v49, v169 dst_sel:DWORD dst_unused:UNUSED_PAD src0_sel:WORD_1
	v_pk_fma_f32 v[48:49], v[54:55], v[98:99], v[48:49]
	s_nop 0
	v_cvt_pk_f16_f32 v57, v48, v49
	v_cvt_f32_f16_e32 v48, v171
	v_cvt_f32_f16_sdwa v49, v171 dst_sel:DWORD dst_unused:UNUSED_PAD src0_sel:WORD_1
	v_pk_fma_f32 v[48:49], v[50:51], v[90:91], v[48:49]
	s_nop 0
	v_cvt_pk_f16_f32 v59, v48, v49
	v_cvt_f32_f16_e32 v48, v164
	v_cvt_f32_f16_sdwa v49, v164 dst_sel:DWORD dst_unused:UNUSED_PAD src0_sel:WORD_1
	global_store_dwordx4 v[60:61], v[56:59], off offset:256
	v_pk_fma_f32 v[44:45], v[44:45], v[116:117], v[48:49]
	s_nop 0
	v_cvt_pk_f16_f32 v48, v44, v45
	v_cvt_f32_f16_e32 v44, v166
	v_cvt_f32_f16_sdwa v45, v166 dst_sel:DWORD dst_unused:UNUSED_PAD src0_sel:WORD_1
	v_pk_fma_f32 v[40:41], v[40:41], v[108:109], v[44:45]
	s_nop 0
	v_cvt_pk_f16_f32 v50, v40, v41
	v_cvt_f32_f16_e32 v40, v165
	v_cvt_f32_f16_sdwa v41, v165 dst_sel:DWORD dst_unused:UNUSED_PAD src0_sel:WORD_1
	v_pk_fma_f32 v[40:41], v[46:47], v[118:119], v[40:41]
	s_nop 0
	v_cvt_pk_f16_f32 v49, v40, v41
	v_cvt_f32_f16_e32 v40, v167
	v_cvt_f32_f16_sdwa v41, v167 dst_sel:DWORD dst_unused:UNUSED_PAD src0_sel:WORD_1
	v_pk_fma_f32 v[40:41], v[42:43], v[110:111], v[40:41]
	s_nop 0
	v_cvt_pk_f16_f32 v51, v40, v41
	v_lshl_add_u64 v[40:41], s[56:57], 0, v[226:227]
	v_lshl_add_u64 v[44:45], v[40:41], 0, v[220:221]
	v_cvt_f32_f16_e32 v40, v152
	v_cvt_f32_f16_sdwa v41, v152 dst_sel:DWORD dst_unused:UNUSED_PAD src0_sel:WORD_1
	global_store_dwordx4 v[44:45], v[48:51], off
	v_pk_fma_f32 v[36:37], v[36:37], v[96:97], v[40:41]
	s_nop 0
	v_cvt_pk_f16_f32 v40, v36, v37
	v_cvt_f32_f16_e32 v36, v154
	v_cvt_f32_f16_sdwa v37, v154 dst_sel:DWORD dst_unused:UNUSED_PAD src0_sel:WORD_1
	v_pk_fma_f32 v[32:33], v[32:33], v[88:89], v[36:37]
	s_nop 0
	v_cvt_pk_f16_f32 v42, v32, v33
	v_cvt_f32_f16_e32 v32, v153
	v_cvt_f32_f16_sdwa v33, v153 dst_sel:DWORD dst_unused:UNUSED_PAD src0_sel:WORD_1
	v_pk_fma_f32 v[32:33], v[38:39], v[98:99], v[32:33]
	s_nop 0
	v_cvt_pk_f16_f32 v41, v32, v33
	v_cvt_f32_f16_e32 v32, v155
	v_cvt_f32_f16_sdwa v33, v155 dst_sel:DWORD dst_unused:UNUSED_PAD src0_sel:WORD_1
	v_pk_fma_f32 v[32:33], v[34:35], v[90:91], v[32:33]
	s_nop 0
	v_cvt_pk_f16_f32 v43, v32, v33
	v_cvt_f32_f16_e32 v32, v148
	v_cvt_f32_f16_sdwa v33, v148 dst_sel:DWORD dst_unused:UNUSED_PAD src0_sel:WORD_1
	global_store_dwordx4 v[44:45], v[40:43], off offset:256
	v_pk_fma_f32 v[28:29], v[28:29], v[116:117], v[32:33]
	s_nop 0
	v_cvt_pk_f16_f32 v32, v28, v29
	v_cvt_f32_f16_e32 v28, v150
	v_cvt_f32_f16_sdwa v29, v150 dst_sel:DWORD dst_unused:UNUSED_PAD src0_sel:WORD_1
	v_pk_fma_f32 v[24:25], v[24:25], v[108:109], v[28:29]
	s_nop 0
	v_cvt_pk_f16_f32 v34, v24, v25
	v_cvt_f32_f16_e32 v24, v149
	v_cvt_f32_f16_sdwa v25, v149 dst_sel:DWORD dst_unused:UNUSED_PAD src0_sel:WORD_1
	v_pk_fma_f32 v[24:25], v[30:31], v[118:119], v[24:25]
	s_nop 0
	v_cvt_pk_f16_f32 v33, v24, v25
	v_cvt_f32_f16_e32 v24, v151
	v_cvt_f32_f16_sdwa v25, v151 dst_sel:DWORD dst_unused:UNUSED_PAD src0_sel:WORD_1
	v_pk_fma_f32 v[24:25], v[26:27], v[110:111], v[24:25]
	s_nop 0
	v_cvt_pk_f16_f32 v35, v24, v25
	v_lshl_add_u64 v[24:25], s[56:57], 0, v[224:225]
	v_lshl_add_u64 v[28:29], v[24:25], 0, v[220:221]
	v_cvt_f32_f16_e32 v24, v144
	v_cvt_f32_f16_sdwa v25, v144 dst_sel:DWORD dst_unused:UNUSED_PAD src0_sel:WORD_1
	global_store_dwordx4 v[28:29], v[32:35], off
	v_pk_fma_f32 v[20:21], v[20:21], v[96:97], v[24:25]
	s_nop 0
	v_cvt_pk_f16_f32 v24, v20, v21
	v_cvt_f32_f16_e32 v20, v146
	v_cvt_f32_f16_sdwa v21, v146 dst_sel:DWORD dst_unused:UNUSED_PAD src0_sel:WORD_1
	v_pk_fma_f32 v[16:17], v[16:17], v[88:89], v[20:21]
	s_nop 0
	v_cvt_pk_f16_f32 v26, v16, v17
	v_cvt_f32_f16_e32 v16, v145
	v_cvt_f32_f16_sdwa v17, v145 dst_sel:DWORD dst_unused:UNUSED_PAD src0_sel:WORD_1
	v_pk_fma_f32 v[16:17], v[22:23], v[98:99], v[16:17]
	s_nop 0
	v_cvt_pk_f16_f32 v25, v16, v17
	v_cvt_f32_f16_e32 v16, v147
	v_cvt_f32_f16_sdwa v17, v147 dst_sel:DWORD dst_unused:UNUSED_PAD src0_sel:WORD_1
	v_pk_fma_f32 v[16:17], v[18:19], v[90:91], v[16:17]
	s_nop 0
	v_cvt_pk_f16_f32 v27, v16, v17
	v_cvt_f32_f16_e32 v16, v136
	v_cvt_f32_f16_sdwa v17, v136 dst_sel:DWORD dst_unused:UNUSED_PAD src0_sel:WORD_1
	global_store_dwordx4 v[28:29], v[24:27], off offset:256
	v_pk_fma_f32 v[12:13], v[12:13], v[116:117], v[16:17]
	s_nop 0
	v_cvt_pk_f16_f32 v16, v12, v13
	v_cvt_f32_f16_e32 v12, v138
	v_cvt_f32_f16_sdwa v13, v138 dst_sel:DWORD dst_unused:UNUSED_PAD src0_sel:WORD_1
	v_pk_fma_f32 v[8:9], v[8:9], v[108:109], v[12:13]
	s_nop 0
	v_cvt_pk_f16_f32 v18, v8, v9
	v_cvt_f32_f16_e32 v8, v137
	v_cvt_f32_f16_sdwa v9, v137 dst_sel:DWORD dst_unused:UNUSED_PAD src0_sel:WORD_1
	v_pk_fma_f32 v[8:9], v[14:15], v[118:119], v[8:9]
	s_nop 0
	v_cvt_pk_f16_f32 v17, v8, v9
	v_cvt_f32_f16_e32 v8, v139
	v_cvt_f32_f16_sdwa v9, v139 dst_sel:DWORD dst_unused:UNUSED_PAD src0_sel:WORD_1
	v_pk_fma_f32 v[8:9], v[10:11], v[110:111], v[8:9]
	s_nop 0
	v_cvt_pk_f16_f32 v19, v8, v9
	v_lshl_add_u64 v[8:9], s[56:57], 0, v[222:223]
	v_lshl_add_u64 v[12:13], v[8:9], 0, v[220:221]
	v_cvt_f32_f16_e32 v8, v128
	v_cvt_f32_f16_sdwa v9, v128 dst_sel:DWORD dst_unused:UNUSED_PAD src0_sel:WORD_1
	global_store_dwordx4 v[12:13], v[16:19], off
	v_pk_fma_f32 v[4:5], v[4:5], v[96:97], v[8:9]
	s_nop 0
	v_cvt_pk_f16_f32 v8, v4, v5
	v_cvt_f32_f16_e32 v4, v130
	v_cvt_f32_f16_sdwa v5, v130 dst_sel:DWORD dst_unused:UNUSED_PAD src0_sel:WORD_1
	v_pk_fma_f32 v[0:1], v[0:1], v[88:89], v[4:5]
	s_nop 0
	v_cvt_pk_f16_f32 v10, v0, v1
	v_cvt_f32_f16_e32 v0, v129
	v_cvt_f32_f16_sdwa v1, v129 dst_sel:DWORD dst_unused:UNUSED_PAD src0_sel:WORD_1
	v_pk_fma_f32 v[0:1], v[6:7], v[98:99], v[0:1]
	s_nop 0
	v_cvt_pk_f16_f32 v9, v0, v1
	v_cvt_f32_f16_e32 v0, v131
	v_cvt_f32_f16_sdwa v1, v131 dst_sel:DWORD dst_unused:UNUSED_PAD src0_sel:WORD_1
	v_pk_fma_f32 v[0:1], v[2:3], v[90:91], v[0:1]
	s_nop 0
	v_cvt_pk_f16_f32 v11, v0, v1
	global_store_dwordx4 v[12:13], v[8:11], off offset:256
	s_cbranch_vccz .LBB0_1178
	s_waitcnt vmcnt(0)
	s_cmpk_gt_u32 s34, 0xff
	s_cbranch_scc1 .LBB0_1189
	s_barrier
